# pre-MMA hand-over only: setprio before the barrier, redundant lgkmcnt(0) removed
# baseline (speedup 1.0000x reference)
; #define PG8_STAGE(bufoff, gbase, voff) do { _Pragma("unroll") for (int _i = 0; _i < 2; ++_i) \
;         __builtin_amdgcn_global_load_lds((const unsigned*)((const char*)(gbase) + (voff)[_i]), (PG8_LAS unsigned*)(lds + (bufoff) + ldsw + _i * 8192), 16, 0, 0); } while (0)
; #define PG8_LDA(dst, b, h) do { _Pragma("unroll") for (int m = 0; m < 4; ++m) _Pragma("unroll") for (int k = 0; k < 2; ++k) dst[m][k] = *(const PG8_LAS bf16x8*)(lds + PG8_SA(b, h) + aoff + m * 2048 + k * 1024); } while (0)
; #define PG8_LDB(dst, b, h) do { _Pragma("unroll") for (int n = 0; n < 2; ++n) _Pragma("unroll") for (int k = 0; k < 2; ++k) dst[n][k] = *(const PG8_LAS bf16x8*)(lds + PG8_SB(b, h) + boff + n * 2048 + k * 1024); } while (0)
; #define PG8_MMA(ai, bj, At, Bt) do { __builtin_amdgcn_s_setprio(1); _Pragma("unroll") for (int m = 0; m < 4; ++m) _Pragma("unroll") for (int n = 0; n < 2; ++n) _Pragma("unroll") for (int k = 0; k < 2; ++k) \
;         acc[ai][bj][m][n] = __builtin_amdgcn_mfma_f32_16x16x32_bf16(Bt[n][k], At[m][k], acc[ai][bj][m][n], 0, 0, 0); __builtin_amdgcn_s_setprio(0); } while (0)
; #define PG8_WAIT_V(n) asm volatile("s_waitcnt vmcnt(" #n ")" ::: "memory")
; #define PG8_WAIT_L(n) asm volatile("s_waitcnt lgkmcnt(" #n ")" ::: "memory")
; #define PG8_BAR __builtin_amdgcn_s_barrier()
; #define PG8_SCHED __builtin_amdgcn_sched_barrier(0)
; template <class Epi, class Sched, bool ALIGN_EPI = false, bool SP2 = false>
; __device__ __forceinline__ void gemm_phase(PG8_LAS unsigned char* lds, const Gemm g, const Sched& S, const Epi& E) {
;     ...
;             PG8_LDB(B0, 0, 0); PG8_LDB(B1, 0, 1); PG8_SCHED; PG8_LDA(At, 0, 0); PG8_STAGE(PG8_SA(1, 1), a1 + hstep, voffA);
;             PG8_WAIT_V(8); PG8_WAIT_L(0); PG8_BAR; PG8_MMA(0, 0, At, B0); PG8_MMA(0, 1, At, B1); PG8_BAR; PG8_SCHED;
;             PG8_LDA(At, 0, 1); PG8_STAGE(PG8_SB(0, 0), b2, voffB); PG8_STAGE(PG8_SB(0, 1), b2 + hstep, voffB); PG8_STAGE(PG8_SA(0, 0), a2, voffA);
;             PG8_WAIT_V(8); PG8_WAIT_L(0); PG8_BAR; PG8_MMA(1, 0, At, B0); PG8_MMA(1, 1, At, B1); PG8_BAR; PG8_SCHED;
.LBB0_132:
	ds_read_b128 v[152:155], v171
	ds_read_b128 v[176:179], v171 offset:1024
	ds_read_b128 v[180:183], v171 offset:2048
	ds_read_b128 v[184:187], v171 offset:3072
	ds_read_b128 v[188:191], v172
	ds_read_b128 v[192:195], v172 offset:1024
	ds_read_b128 v[198:201], v172 offset:2048
	ds_read_b128 v[202:205], v172 offset:3072
	s_add_u32 s46, s2, 0xfff00080
	s_addc_u32 s47, s3, -1
	s_cmp_eq_u32 s82, 60
	s_cselect_b32 s49, s35, s47
	s_cselect_b32 s48, s43, s46
	s_cselect_b32 s47, s17, s81
	s_cselect_b32 s46, s79, s80
	v_lshl_add_u64 v[156:157], s[2:3], 0, v[144:145]
	s_add_i32 m0, s45, 0xc000
	ds_read_b128 v[206:209], v173
	ds_read_b128 v[210:213], v173 offset:1024
	ds_read_b128 v[214:217], v173 offset:2048
	ds_read_b128 v[218:221], v173 offset:3072
	ds_read_b128 v[222:225], v173 offset:4096
	ds_read_b128 v[226:229], v173 offset:5120
	ds_read_b128 v[230:233], v173 offset:6144
	ds_read_b128 v[234:237], v173 offset:7168
	global_load_lds_dwordx4 v[156:157], off
	v_lshl_add_u64 v[156:157], s[2:3], 0, v[146:147]
	s_add_i32 m0, s45, 0xe000
	s_nop 0
	global_load_lds_dwordx4 v[156:157], off
	s_waitcnt vmcnt(8)
	s_waitcnt lgkmcnt(0)
	s_setprio 1
	s_barrier
	v_mfma_f32_16x16x32_bf16 v[126:129], v[152:155], v[206:209], v[126:129]
	v_mfma_f32_16x16x32_bf16 v[122:125], v[180:183], v[206:209], v[122:125]
	v_mfma_f32_16x16x32_bf16 v[110:113], v[152:155], v[214:217], v[110:113]
	v_mfma_f32_16x16x32_bf16 v[106:109], v[180:183], v[214:217], v[106:109]
	v_mfma_f32_16x16x32_bf16 v[94:97], v[152:155], v[222:225], v[94:97]
	v_mfma_f32_16x16x32_bf16 v[90:93], v[180:183], v[222:225], v[90:93]
	v_mfma_f32_16x16x32_bf16 v[78:81], v[152:155], v[230:233], v[78:81]
	v_mfma_f32_16x16x32_bf16 v[74:77], v[180:183], v[230:233], v[74:77]
	v_mfma_f32_16x16x32_bf16 v[126:129], v[176:179], v[210:213], v[126:129]
	v_mfma_f32_16x16x32_bf16 v[122:125], v[184:187], v[210:213], v[122:125]
	v_mfma_f32_16x16x32_bf16 v[110:113], v[176:179], v[218:221], v[110:113]
	v_mfma_f32_16x16x32_bf16 v[106:109], v[184:187], v[218:221], v[106:109]
	v_mfma_f32_16x16x32_bf16 v[94:97], v[176:179], v[226:229], v[94:97]
	v_mfma_f32_16x16x32_bf16 v[90:93], v[184:187], v[226:229], v[90:93]
	v_mfma_f32_16x16x32_bf16 v[78:81], v[176:179], v[234:237], v[78:81]
	v_mfma_f32_16x16x32_bf16 v[74:77], v[184:187], v[234:237], v[74:77]
	s_setprio 0
	s_setprio 1
	v_mfma_f32_16x16x32_bf16 v[118:121], v[188:191], v[206:209], v[118:121]
	v_mfma_f32_16x16x32_bf16 v[114:117], v[198:201], v[206:209], v[114:117]
	v_mfma_f32_16x16x32_bf16 v[102:105], v[188:191], v[214:217], v[102:105]
	v_mfma_f32_16x16x32_bf16 v[98:101], v[198:201], v[214:217], v[98:101]
	v_mfma_f32_16x16x32_bf16 v[86:89], v[188:191], v[222:225], v[86:89]
	v_mfma_f32_16x16x32_bf16 v[82:85], v[198:201], v[222:225], v[82:85]
	v_mfma_f32_16x16x32_bf16 v[70:73], v[188:191], v[230:233], v[70:73]
	v_mfma_f32_16x16x32_bf16 v[66:69], v[198:201], v[230:233], v[66:69]
	v_mfma_f32_16x16x32_bf16 v[118:121], v[192:195], v[210:213], v[118:121]
	v_mfma_f32_16x16x32_bf16 v[114:117], v[202:205], v[210:213], v[114:117]
	v_mfma_f32_16x16x32_bf16 v[102:105], v[192:195], v[218:221], v[102:105]
	v_mfma_f32_16x16x32_bf16 v[98:101], v[202:205], v[218:221], v[98:101]
	v_mfma_f32_16x16x32_bf16 v[86:89], v[192:195], v[226:229], v[86:89]
	v_mfma_f32_16x16x32_bf16 v[82:85], v[202:205], v[226:229], v[82:85]
	v_mfma_f32_16x16x32_bf16 v[70:73], v[192:195], v[234:237], v[70:73]
	v_mfma_f32_16x16x32_bf16 v[66:69], v[202:205], v[234:237], v[66:69]
	s_setprio 0
	s_barrier
	s_add_i32 s83, s74, s55
	v_lshl_add_u64 v[156:157], s[46:47], 0, v[132:133]
	s_mov_b32 m0, s83
	ds_read_b128 v[206:209], v173 offset:16384
	ds_read_b128 v[210:213], v173 offset:17408
	ds_read_b128 v[214:217], v173 offset:18432
	ds_read_b128 v[218:221], v173 offset:19456
	ds_read_b128 v[222:225], v173 offset:20480
	ds_read_b128 v[226:229], v173 offset:21504
	ds_read_b128 v[230:233], v173 offset:22528
	ds_read_b128 v[234:237], v173 offset:23552
	global_load_lds_dwordx4 v[156:157], off
	s_add_i32 m0, s83, 0x2000
	s_add_u32 s84, s46, 0x100000
	v_lshl_add_u64 v[238:239], s[46:47], 0, v[136:137]
	s_addc_u32 s85, s47, 0
	s_add_i32 s83, s75, s55
	global_load_lds_dwordx4 v[238:239], off
	v_lshl_add_u64 v[240:241], s[84:85], 0, v[132:133]
	s_mov_b32 m0, s83
	v_lshl_add_u64 v[242:243], s[48:49], 0, v[134:135]
	global_load_lds_dwordx4 v[240:241], off
	v_lshl_add_u64 v[240:241], s[84:85], 0, v[136:137]
	s_add_i32 m0, s83, 0x2000
	s_nop 0
	global_load_lds_dwordx4 v[240:241], off
	v_lshl_add_u64 v[240:241], s[48:49], 0, v[130:131]
	s_mov_b32 m0, s45
	s_nop 0
	global_load_lds_dwordx4 v[240:241], off
	s_mov_b32 m0, s56
	s_nop 0
	global_load_lds_dwordx4 v[242:243], off
	s_waitcnt vmcnt(8)
	s_waitcnt lgkmcnt(0)
	s_setprio 1
	s_barrier
; #define PG8_STAGE(bufoff, gbase, voff) do { _Pragma("unroll") for (int _i = 0; _i < 2; ++_i) \
;         __builtin_amdgcn_global_load_lds((const unsigned*)((const char*)(gbase) + (voff)[_i]), (PG8_LAS unsigned*)(lds + (bufoff) + ldsw + _i * 8192), 16, 0, 0); } while (0)
; #define PG8_LDA(dst, b, h) do { _Pragma("unroll") for (int m = 0; m < 4; ++m) _Pragma("unroll") for (int k = 0; k < 2; ++k) dst[m][k] = *(const PG8_LAS bf16x8*)(lds + PG8_SA(b, h) + aoff + m * 2048 + k * 1024); } while (0)
; #define PG8_LDB(dst, b, h) do { _Pragma("unroll") for (int n = 0; n < 2; ++n) _Pragma("unroll") for (int k = 0; k < 2; ++k) dst[n][k] = *(const PG8_LAS bf16x8*)(lds + PG8_SB(b, h) + boff + n * 2048 + k * 1024); } while (0)
; #define PG8_MMA(ai, bj, At, Bt) do { __builtin_amdgcn_s_setprio(1); _Pragma("unroll") for (int m = 0; m < 4; ++m) _Pragma("unroll") for (int n = 0; n < 2; ++n) _Pragma("unroll") for (int k = 0; k < 2; ++k) \
;         acc[ai][bj][m][n] = __builtin_amdgcn_mfma_f32_16x16x32_bf16(Bt[n][k], At[m][k], acc[ai][bj][m][n], 0, 0, 0); __builtin_amdgcn_s_setprio(0); } while (0)
; #define PG8_WAIT_V(n) asm volatile("s_waitcnt vmcnt(" #n ")" ::: "memory")
; #define PG8_WAIT_L(n) asm volatile("s_waitcnt lgkmcnt(" #n ")" ::: "memory")
; #define PG8_BAR __builtin_amdgcn_s_barrier()
; #define PG8_SCHED __builtin_amdgcn_sched_barrier(0)
; template <class Epi, class Sched, bool ALIGN_EPI = false, bool SP2 = false>
; __device__ __forceinline__ void gemm_phase(PG8_LAS unsigned char* lds, const Gemm g, const Sched& S, const Epi& E) {
;     ...
;             PG8_WAIT_V(8); PG8_WAIT_L(0); PG8_BAR; PG8_MMA(1, 0, At, B0); PG8_MMA(1, 1, At, B1); PG8_BAR; PG8_SCHED;
;             PG8_LDB(B0, 1, 0); PG8_LDB(B1, 1, 1); PG8_SCHED; PG8_LDA(At, 1, 0); PG8_STAGE(PG8_SA(0, 1), a2 + hstep, voffA);
;             PG8_WAIT_V(8); PG8_WAIT_L(0); PG8_BAR; PG8_MMA(0, 0, At, B0); PG8_MMA(0, 1, At, B1); PG8_BAR; PG8_SCHED;
	v_mfma_f32_16x16x32_bf16 v[62:65], v[152:155], v[206:209], v[62:65]
	v_mfma_f32_16x16x32_bf16 v[58:61], v[180:183], v[206:209], v[58:61]
	v_mfma_f32_16x16x32_bf16 v[46:49], v[152:155], v[214:217], v[46:49]
	v_mfma_f32_16x16x32_bf16 v[42:45], v[180:183], v[214:217], v[42:45]
	v_mfma_f32_16x16x32_bf16 v[30:33], v[152:155], v[222:225], v[30:33]
	v_mfma_f32_16x16x32_bf16 v[26:29], v[180:183], v[222:225], v[26:29]
	v_mfma_f32_16x16x32_bf16 v[14:17], v[152:155], v[230:233], v[14:17]
	v_mfma_f32_16x16x32_bf16 v[10:13], v[180:183], v[230:233], v[10:13]
	v_mfma_f32_16x16x32_bf16 v[62:65], v[176:179], v[210:213], v[62:65]
	v_mfma_f32_16x16x32_bf16 v[58:61], v[184:187], v[210:213], v[58:61]
	v_mfma_f32_16x16x32_bf16 v[46:49], v[176:179], v[218:221], v[46:49]
	v_mfma_f32_16x16x32_bf16 v[42:45], v[184:187], v[218:221], v[42:45]
	v_mfma_f32_16x16x32_bf16 v[30:33], v[176:179], v[226:229], v[30:33]
	v_mfma_f32_16x16x32_bf16 v[26:29], v[184:187], v[226:229], v[26:29]
	v_mfma_f32_16x16x32_bf16 v[14:17], v[176:179], v[234:237], v[14:17]
	v_mfma_f32_16x16x32_bf16 v[10:13], v[184:187], v[234:237], v[10:13]
	s_setprio 0
	s_setprio 1
	v_mfma_f32_16x16x32_bf16 v[54:57], v[188:191], v[206:209], v[54:57]
	v_mfma_f32_16x16x32_bf16 v[50:53], v[198:201], v[206:209], v[50:53]
	v_mfma_f32_16x16x32_bf16 v[38:41], v[188:191], v[214:217], v[38:41]
	v_mfma_f32_16x16x32_bf16 v[34:37], v[198:201], v[214:217], v[34:37]
	v_mfma_f32_16x16x32_bf16 v[22:25], v[188:191], v[222:225], v[22:25]
	v_mfma_f32_16x16x32_bf16 v[18:21], v[198:201], v[222:225], v[18:21]
	v_mfma_f32_16x16x32_bf16 v[6:9], v[188:191], v[230:233], v[6:9]
	v_mfma_f32_16x16x32_bf16 v[2:5], v[198:201], v[230:233], v[2:5]
	v_mfma_f32_16x16x32_bf16 v[54:57], v[192:195], v[210:213], v[54:57]
	v_mfma_f32_16x16x32_bf16 v[50:53], v[202:205], v[210:213], v[50:53]
	v_mfma_f32_16x16x32_bf16 v[38:41], v[192:195], v[218:221], v[38:41]
	v_mfma_f32_16x16x32_bf16 v[34:37], v[202:205], v[218:221], v[34:37]
	v_mfma_f32_16x16x32_bf16 v[22:25], v[192:195], v[226:229], v[22:25]
	v_mfma_f32_16x16x32_bf16 v[18:21], v[202:205], v[226:229], v[18:21]
	v_mfma_f32_16x16x32_bf16 v[6:9], v[192:195], v[234:237], v[6:9]
	v_mfma_f32_16x16x32_bf16 v[2:5], v[202:205], v[234:237], v[2:5]
	s_setprio 0
	s_barrier
	s_add_i32 s83, 0, 0x18000
	v_add_u32_e32 v149, s83, v167
	s_add_i32 s84, 0, 0x1c000
	ds_read_b128 v[152:155], v149
	ds_read_b128 v[176:179], v149 offset:1024
	ds_read_b128 v[180:183], v149 offset:2048
	ds_read_b128 v[184:187], v149 offset:3072
	v_add_u32_e32 v149, s84, v167
	ds_read_b128 v[188:191], v149
	ds_read_b128 v[192:195], v149 offset:1024
	ds_read_b128 v[198:201], v149 offset:2048
	ds_read_b128 v[202:205], v149 offset:3072
	s_add_u32 s48, s48, 0x100000
	s_addc_u32 s49, s49, 0
	s_mov_b32 m0, s57
	v_lshl_add_u64 v[244:245], s[48:49], 0, v[130:131]
	ds_read_b128 v[206:209], v173 offset:32768
	ds_read_b128 v[210:213], v173 offset:33792
	ds_read_b128 v[214:217], v173 offset:34816
	ds_read_b128 v[218:221], v173 offset:35840
	ds_read_b128 v[222:225], v173 offset:36864
	ds_read_b128 v[226:229], v173 offset:37888
	ds_read_b128 v[230:233], v173 offset:38912
	ds_read_b128 v[234:237], v173 offset:39936
	global_load_lds_dwordx4 v[244:245], off
	v_lshl_add_u64 v[244:245], s[48:49], 0, v[134:135]
	s_mov_b32 m0, s58
	s_nop 0
	global_load_lds_dwordx4 v[244:245], off
	s_waitcnt vmcnt(8)
	s_waitcnt lgkmcnt(0)
	s_setprio 1
	s_barrier
	v_mfma_f32_16x16x32_bf16 v[126:129], v[152:155], v[206:209], v[126:129]
	v_mfma_f32_16x16x32_bf16 v[122:125], v[180:183], v[206:209], v[122:125]
	v_mfma_f32_16x16x32_bf16 v[110:113], v[152:155], v[214:217], v[110:113]
	v_mfma_f32_16x16x32_bf16 v[106:109], v[180:183], v[214:217], v[106:109]
	v_mfma_f32_16x16x32_bf16 v[94:97], v[152:155], v[222:225], v[94:97]
	v_mfma_f32_16x16x32_bf16 v[90:93], v[180:183], v[222:225], v[90:93]
	v_mfma_f32_16x16x32_bf16 v[78:81], v[152:155], v[230:233], v[78:81]
	v_mfma_f32_16x16x32_bf16 v[74:77], v[180:183], v[230:233], v[74:77]
	v_mfma_f32_16x16x32_bf16 v[126:129], v[176:179], v[210:213], v[126:129]
	v_mfma_f32_16x16x32_bf16 v[122:125], v[184:187], v[210:213], v[122:125]
	v_mfma_f32_16x16x32_bf16 v[110:113], v[176:179], v[218:221], v[110:113]
	v_mfma_f32_16x16x32_bf16 v[106:109], v[184:187], v[218:221], v[106:109]
	v_mfma_f32_16x16x32_bf16 v[94:97], v[176:179], v[226:229], v[94:97]
	v_mfma_f32_16x16x32_bf16 v[90:93], v[184:187], v[226:229], v[90:93]
	v_mfma_f32_16x16x32_bf16 v[78:81], v[176:179], v[234:237], v[78:81]
	v_mfma_f32_16x16x32_bf16 v[74:77], v[184:187], v[234:237], v[74:77]
	s_setprio 0
	s_setprio 1
	v_mfma_f32_16x16x32_bf16 v[118:121], v[188:191], v[206:209], v[118:121]
	v_mfma_f32_16x16x32_bf16 v[114:117], v[198:201], v[206:209], v[114:117]
	v_mfma_f32_16x16x32_bf16 v[102:105], v[188:191], v[214:217], v[102:105]
	v_mfma_f32_16x16x32_bf16 v[98:101], v[198:201], v[214:217], v[98:101]
	v_mfma_f32_16x16x32_bf16 v[86:89], v[188:191], v[222:225], v[86:89]
	v_mfma_f32_16x16x32_bf16 v[82:85], v[198:201], v[222:225], v[82:85]
	v_mfma_f32_16x16x32_bf16 v[70:73], v[188:191], v[230:233], v[70:73]
	v_mfma_f32_16x16x32_bf16 v[66:69], v[198:201], v[230:233], v[66:69]
	v_mfma_f32_16x16x32_bf16 v[118:121], v[192:195], v[210:213], v[118:121]
	v_mfma_f32_16x16x32_bf16 v[114:117], v[202:205], v[210:213], v[114:117]
	v_mfma_f32_16x16x32_bf16 v[102:105], v[192:195], v[218:221], v[102:105]
	v_mfma_f32_16x16x32_bf16 v[98:101], v[202:205], v[218:221], v[98:101]
	v_mfma_f32_16x16x32_bf16 v[86:89], v[192:195], v[226:229], v[86:89]
	v_mfma_f32_16x16x32_bf16 v[82:85], v[202:205], v[226:229], v[82:85]
	v_mfma_f32_16x16x32_bf16 v[70:73], v[192:195], v[234:237], v[70:73]
	v_mfma_f32_16x16x32_bf16 v[66:69], v[202:205], v[234:237], v[66:69]
	s_setprio 0
	s_barrier
; #define PG8_STAGE(bufoff, gbase, voff) do { _Pragma("unroll") for (int _i = 0; _i < 2; ++_i) \
;         __builtin_amdgcn_global_load_lds((const unsigned*)((const char*)(gbase) + (voff)[_i]), (PG8_LAS unsigned*)(lds + (bufoff) + ldsw + _i * 8192), 16, 0, 0); } while (0)
; #define PG8_LDA(dst, b, h) do { _Pragma("unroll") for (int m = 0; m < 4; ++m) _Pragma("unroll") for (int k = 0; k < 2; ++k) dst[m][k] = *(const PG8_LAS bf16x8*)(lds + PG8_SA(b, h) + aoff + m * 2048 + k * 1024); } while (0)
; #define PG8_MMA(ai, bj, At, Bt) do { __builtin_amdgcn_s_setprio(1); _Pragma("unroll") for (int m = 0; m < 4; ++m) _Pragma("unroll") for (int n = 0; n < 2; ++n) _Pragma("unroll") for (int k = 0; k < 2; ++k) \
;         acc[ai][bj][m][n] = __builtin_amdgcn_mfma_f32_16x16x32_bf16(Bt[n][k], At[m][k], acc[ai][bj][m][n], 0, 0, 0); __builtin_amdgcn_s_setprio(0); } while (0)
; #define PG8_WAIT_V(n) asm volatile("s_waitcnt vmcnt(" #n ")" ::: "memory")
; #define PG8_WAIT_L(n) asm volatile("s_waitcnt lgkmcnt(" #n ")" ::: "memory")
; #define PG8_BAR __builtin_amdgcn_s_barrier()
; #define PG8_SCHED __builtin_amdgcn_sched_barrier(0)
; template <class Epi, class Sched, bool ALIGN_EPI = false, bool SP2 = false>
; __device__ __forceinline__ void gemm_phase(PG8_LAS unsigned char* lds, const Gemm g, const Sched& S, const Epi& E) {
;     ...
;             PG8_LDA(At, 1, 1); PG8_STAGE(PG8_SB(1, 0), b3, voffB); PG8_STAGE(PG8_SB(1, 1), b3 + hstep, voffB); PG8_STAGE(PG8_SA(1, 0), a3, voffA);
;             PG8_WAIT_V(8); PG8_WAIT_L(0); PG8_BAR; PG8_MMA(1, 0, At, B0); PG8_MMA(1, 1, At, B1); PG8_BAR; PG8_SCHED;
;     ...
;         if constexpr (ALIGN_EPI) { if (wr == 0) PG8_BAR; }
	s_add_i32 s48, s83, s55
	v_lshl_add_u64 v[156:157], v[156:157], 0, s[10:11]
	s_mov_b32 m0, s48
	ds_read_b128 v[206:209], v173 offset:49152
	ds_read_b128 v[210:213], v173 offset:50176
	ds_read_b128 v[214:217], v173 offset:51200
	ds_read_b128 v[218:221], v173 offset:52224
	ds_read_b128 v[222:225], v173 offset:53248
	ds_read_b128 v[226:229], v173 offset:54272
	ds_read_b128 v[230:233], v173 offset:55296
	ds_read_b128 v[234:237], v173 offset:56320
	global_load_lds_dwordx4 v[156:157], off
	s_add_i32 m0, s48, 0x2000
	s_add_u32 s46, s46, 0x100080
	v_lshl_add_u64 v[156:157], v[238:239], 0, s[10:11]
	s_addc_u32 s47, s47, 0
	s_add_i32 s48, s84, s55
	global_load_lds_dwordx4 v[156:157], off
	v_lshl_add_u64 v[156:157], s[46:47], 0, v[132:133]
	s_mov_b32 m0, s48
	s_nop 0
	global_load_lds_dwordx4 v[156:157], off
	v_lshl_add_u64 v[156:157], s[46:47], 0, v[136:137]
	s_add_i32 m0, s48, 0x2000
	s_nop 0
	global_load_lds_dwordx4 v[156:157], off
	v_lshl_add_u64 v[156:157], v[240:241], 0, s[10:11]
	s_mov_b32 m0, s63
	s_nop 0
	global_load_lds_dwordx4 v[156:157], off
	v_lshl_add_u64 v[156:157], v[242:243], 0, s[10:11]
	s_mov_b32 m0, s70
	s_nop 0
	global_load_lds_dwordx4 v[156:157], off
	s_waitcnt vmcnt(8)
	s_waitcnt lgkmcnt(0)
	s_setprio 1
	s_barrier
	v_mfma_f32_16x16x32_bf16 v[62:65], v[152:155], v[206:209], v[62:65]
	v_mfma_f32_16x16x32_bf16 v[58:61], v[180:183], v[206:209], v[58:61]
	v_mfma_f32_16x16x32_bf16 v[46:49], v[152:155], v[214:217], v[46:49]
	v_mfma_f32_16x16x32_bf16 v[42:45], v[180:183], v[214:217], v[42:45]
	v_mfma_f32_16x16x32_bf16 v[30:33], v[152:155], v[222:225], v[30:33]
	v_mfma_f32_16x16x32_bf16 v[26:29], v[180:183], v[222:225], v[26:29]
	v_mfma_f32_16x16x32_bf16 v[14:17], v[152:155], v[230:233], v[14:17]
	v_mfma_f32_16x16x32_bf16 v[10:13], v[180:183], v[230:233], v[10:13]
	v_mfma_f32_16x16x32_bf16 v[62:65], v[176:179], v[210:213], v[62:65]
	v_mfma_f32_16x16x32_bf16 v[58:61], v[184:187], v[210:213], v[58:61]
	v_mfma_f32_16x16x32_bf16 v[46:49], v[176:179], v[218:221], v[46:49]
	v_mfma_f32_16x16x32_bf16 v[42:45], v[184:187], v[218:221], v[42:45]
	v_mfma_f32_16x16x32_bf16 v[30:33], v[176:179], v[226:229], v[30:33]
	v_mfma_f32_16x16x32_bf16 v[26:29], v[184:187], v[226:229], v[26:29]
	v_mfma_f32_16x16x32_bf16 v[14:17], v[176:179], v[234:237], v[14:17]
	v_mfma_f32_16x16x32_bf16 v[10:13], v[184:187], v[234:237], v[10:13]
	s_setprio 0
	s_setprio 1
	v_mfma_f32_16x16x32_bf16 v[54:57], v[188:191], v[206:209], v[54:57]
	v_mfma_f32_16x16x32_bf16 v[50:53], v[198:201], v[206:209], v[50:53]
	v_mfma_f32_16x16x32_bf16 v[38:41], v[188:191], v[214:217], v[38:41]
	v_mfma_f32_16x16x32_bf16 v[34:37], v[198:201], v[214:217], v[34:37]
	v_mfma_f32_16x16x32_bf16 v[22:25], v[188:191], v[222:225], v[22:25]
	v_mfma_f32_16x16x32_bf16 v[18:21], v[198:201], v[222:225], v[18:21]
	v_mfma_f32_16x16x32_bf16 v[6:9], v[188:191], v[230:233], v[6:9]
	v_mfma_f32_16x16x32_bf16 v[2:5], v[198:201], v[230:233], v[2:5]
	v_mfma_f32_16x16x32_bf16 v[54:57], v[192:195], v[210:213], v[54:57]
	v_mfma_f32_16x16x32_bf16 v[50:53], v[202:205], v[210:213], v[50:53]
	v_mfma_f32_16x16x32_bf16 v[38:41], v[192:195], v[218:221], v[38:41]
	v_mfma_f32_16x16x32_bf16 v[34:37], v[202:205], v[218:221], v[34:37]
	v_mfma_f32_16x16x32_bf16 v[22:25], v[192:195], v[226:229], v[22:25]
	v_mfma_f32_16x16x32_bf16 v[18:21], v[202:205], v[226:229], v[18:21]
	v_mfma_f32_16x16x32_bf16 v[6:9], v[192:195], v[234:237], v[6:9]
	v_mfma_f32_16x16x32_bf16 v[2:5], v[202:205], v[234:237], v[2:5]
	s_setprio 0
	s_barrier
	s_add_i32 s82, s82, 2
	s_add_u32 s2, s2, 0x100
	s_addc_u32 s3, s3, 0
	s_add_u32 s80, s80, 0x100
	s_addc_u32 s81, s81, 0
	s_cmp_gt_u32 s82, 61
	s_cbranch_scc0 .LBB0_132
	s_and_b64 vcc, exec, s[12:13]
	s_cbranch_vccz .LBB0_135
	s_barrier

; #define PG8_STAGE(bufoff, gbase, voff) do { _Pragma("unroll") for (int _i = 0; _i < 2; ++_i) \
;         __builtin_amdgcn_global_load_lds((const unsigned*)((const char*)(gbase) + (voff)[_i]), (PG8_LAS unsigned*)(lds + (bufoff) + ldsw + _i * 8192), 16, 0, 0); } while (0)
; #define PG8_LDA(dst, b, h) do { _Pragma("unroll") for (int m = 0; m < 4; ++m) _Pragma("unroll") for (int k = 0; k < 2; ++k) dst[m][k] = *(const PG8_LAS bf16x8*)(lds + PG8_SA(b, h) + aoff + m * 2048 + k * 1024); } while (0)
; #define PG8_LDB(dst, b, h) do { _Pragma("unroll") for (int n = 0; n < 2; ++n) _Pragma("unroll") for (int k = 0; k < 2; ++k) dst[n][k] = *(const PG8_LAS bf16x8*)(lds + PG8_SB(b, h) + boff + n * 2048 + k * 1024); } while (0)
; #define PG8_MMA(ai, bj, At, Bt) do { __builtin_amdgcn_s_setprio(1); _Pragma("unroll") for (int m = 0; m < 4; ++m) _Pragma("unroll") for (int n = 0; n < 2; ++n) _Pragma("unroll") for (int k = 0; k < 2; ++k) \
;         acc[ai][bj][m][n] = __builtin_amdgcn_mfma_f32_16x16x32_bf16(Bt[n][k], At[m][k], acc[ai][bj][m][n], 0, 0, 0); __builtin_amdgcn_s_setprio(0); } while (0)
; #define PG8_WAIT_V(n) asm volatile("s_waitcnt vmcnt(" #n ")" ::: "memory")
; #define PG8_WAIT_L(n) asm volatile("s_waitcnt lgkmcnt(" #n ")" ::: "memory")
; template <class Epi, class Sched, bool ALIGN_EPI = false, bool SP2 = false>
; __device__ __forceinline__ void gemm_phase(PG8_LAS unsigned char* lds, const Gemm g, const Sched& S, const Epi& E) {
;     ...
;             const bool last = (t == nt - 2);
;             const char* a1 = cA + (size_t)(t + 1) * kstep;
;             const char* a2 = last ? nA : cA + (size_t)(t + 2) * kstep; const char* b2 = last ? nB : cB + (size_t)(t + 2) * kstep;
;             const char* a3 = a2 + kstep; const char* b3 = b2 + kstep;
;             if (last && has_next) S.a_ready(nxt);
;             if constexpr (SP2) {
;             PG8_LDB(B0, 0, 0); PG8_LDB(B1, 0, 1); PG8_SCHED; PG8_LDA(At, 0, 0); PG8_STAGE(PG8_SA(1, 1), a1 + hstep, voffA);
;             PG8_WAIT_V(8); PG8_WAIT_L(0); PG8_BAR; PG8_MMA(0, 0, At, B0); PG8_MMA(0, 1, At, B1); PG8_BAR; PG8_SCHED;
;             PG8_LDA(At, 0, 1); PG8_STAGE(PG8_SB(0, 0), b2, voffB); PG8_STAGE(PG8_SB(0, 1), b2 + hstep, voffB); PG8_STAGE(PG8_SA(0, 0), a2, voffA);
;             PG8_WAIT_V(8); PG8_WAIT_L(0); PG8_BAR; PG8_MMA(1, 0, At, B0); PG8_MMA(1, 1, At, B1); PG8_BAR; PG8_SCHED;
.LBB0_217:
	ds_read_b128 v[152:155], v159
	ds_read_b128 v[168:171], v159 offset:1024
	ds_read_b128 v[172:175], v159 offset:2048
	ds_read_b128 v[176:179], v159 offset:3072
	ds_read_b128 v[180:183], v160
	ds_read_b128 v[184:187], v160 offset:1024
	ds_read_b128 v[188:191], v160 offset:2048
	ds_read_b128 v[192:195], v160 offset:3072
	s_add_u32 s46, s44, 0xfff00080
	s_addc_u32 s47, s45, -1
	s_cmp_eq_u32 s80, 60
	s_cselect_b32 s49, s3, s47
	s_cselect_b32 s48, s35, s46
	s_cselect_b32 s47, s17, s79
	s_cselect_b32 s46, s43, s78
	v_lshl_add_u64 v[156:157], s[44:45], 0, v[144:145]
	s_add_i32 m0, s56, 0xc000
	ds_read_b128 v[198:201], v161
	ds_read_b128 v[202:205], v161 offset:1024
	ds_read_b128 v[206:209], v161 offset:2048
	ds_read_b128 v[210:213], v161 offset:3072
	ds_read_b128 v[214:217], v161 offset:4096
	ds_read_b128 v[218:221], v161 offset:5120
	ds_read_b128 v[222:225], v161 offset:6144
	ds_read_b128 v[226:229], v161 offset:7168
	global_load_lds_dwordx4 v[156:157], off
	v_lshl_add_u64 v[156:157], s[44:45], 0, v[146:147]
	s_add_i32 m0, s56, 0xe000
	s_nop 0
	global_load_lds_dwordx4 v[156:157], off
	s_waitcnt vmcnt(8)
	s_waitcnt lgkmcnt(0)
	s_setprio 1
	s_barrier
	v_mfma_f32_16x16x32_bf16 v[126:129], v[152:155], v[198:201], v[126:129]
	v_mfma_f32_16x16x32_bf16 v[122:125], v[172:175], v[198:201], v[122:125]
	v_mfma_f32_16x16x32_bf16 v[110:113], v[152:155], v[206:209], v[110:113]
	v_mfma_f32_16x16x32_bf16 v[106:109], v[172:175], v[206:209], v[106:109]
	v_mfma_f32_16x16x32_bf16 v[94:97], v[152:155], v[214:217], v[94:97]
	v_mfma_f32_16x16x32_bf16 v[90:93], v[172:175], v[214:217], v[90:93]
	v_mfma_f32_16x16x32_bf16 v[78:81], v[152:155], v[222:225], v[78:81]
	v_mfma_f32_16x16x32_bf16 v[74:77], v[172:175], v[222:225], v[74:77]
	v_mfma_f32_16x16x32_bf16 v[126:129], v[168:171], v[202:205], v[126:129]
	v_mfma_f32_16x16x32_bf16 v[122:125], v[176:179], v[202:205], v[122:125]
	v_mfma_f32_16x16x32_bf16 v[110:113], v[168:171], v[210:213], v[110:113]
	v_mfma_f32_16x16x32_bf16 v[106:109], v[176:179], v[210:213], v[106:109]
	v_mfma_f32_16x16x32_bf16 v[94:97], v[168:171], v[218:221], v[94:97]
	v_mfma_f32_16x16x32_bf16 v[90:93], v[176:179], v[218:221], v[90:93]
	v_mfma_f32_16x16x32_bf16 v[78:81], v[168:171], v[226:229], v[78:81]
	v_mfma_f32_16x16x32_bf16 v[74:77], v[176:179], v[226:229], v[74:77]
	s_setprio 0
	s_setprio 1
	v_mfma_f32_16x16x32_bf16 v[118:121], v[180:183], v[198:201], v[118:121]
	v_mfma_f32_16x16x32_bf16 v[114:117], v[188:191], v[198:201], v[114:117]
	v_mfma_f32_16x16x32_bf16 v[102:105], v[180:183], v[206:209], v[102:105]
	v_mfma_f32_16x16x32_bf16 v[98:101], v[188:191], v[206:209], v[98:101]
	v_mfma_f32_16x16x32_bf16 v[86:89], v[180:183], v[214:217], v[86:89]
	v_mfma_f32_16x16x32_bf16 v[82:85], v[188:191], v[214:217], v[82:85]
	v_mfma_f32_16x16x32_bf16 v[70:73], v[180:183], v[222:225], v[70:73]
	v_mfma_f32_16x16x32_bf16 v[66:69], v[188:191], v[222:225], v[66:69]
	v_mfma_f32_16x16x32_bf16 v[118:121], v[184:187], v[202:205], v[118:121]
	v_mfma_f32_16x16x32_bf16 v[114:117], v[192:195], v[202:205], v[114:117]
	v_mfma_f32_16x16x32_bf16 v[102:105], v[184:187], v[210:213], v[102:105]
	v_mfma_f32_16x16x32_bf16 v[98:101], v[192:195], v[210:213], v[98:101]
	v_mfma_f32_16x16x32_bf16 v[86:89], v[184:187], v[218:221], v[86:89]
	v_mfma_f32_16x16x32_bf16 v[82:85], v[192:195], v[218:221], v[82:85]
	v_mfma_f32_16x16x32_bf16 v[70:73], v[184:187], v[226:229], v[70:73]
	v_mfma_f32_16x16x32_bf16 v[66:69], v[192:195], v[226:229], v[66:69]
	s_setprio 0
	s_barrier
	s_add_i32 s81, s73, s55
	v_lshl_add_u64 v[156:157], s[46:47], 0, v[132:133]
	s_mov_b32 m0, s81
	ds_read_b128 v[198:201], v161 offset:16384
	ds_read_b128 v[202:205], v161 offset:17408
	ds_read_b128 v[206:209], v161 offset:18432
	ds_read_b128 v[210:213], v161 offset:19456
	ds_read_b128 v[214:217], v161 offset:20480
	ds_read_b128 v[218:221], v161 offset:21504
	ds_read_b128 v[222:225], v161 offset:22528
	ds_read_b128 v[226:229], v161 offset:23552
	global_load_lds_dwordx4 v[156:157], off
	s_add_i32 m0, s81, 0x2000
	s_add_u32 s82, s46, 0x100000
	v_lshl_add_u64 v[230:231], s[46:47], 0, v[136:137]
	s_addc_u32 s83, s47, 0
	s_add_i32 s81, s74, s55
	global_load_lds_dwordx4 v[230:231], off
	v_lshl_add_u64 v[232:233], s[82:83], 0, v[132:133]
	s_mov_b32 m0, s81
	v_lshl_add_u64 v[234:235], s[48:49], 0, v[134:135]
	global_load_lds_dwordx4 v[232:233], off
	v_lshl_add_u64 v[232:233], s[82:83], 0, v[136:137]
	s_add_i32 m0, s81, 0x2000
	s_nop 0
	global_load_lds_dwordx4 v[232:233], off
	v_lshl_add_u64 v[232:233], s[48:49], 0, v[130:131]
	s_mov_b32 m0, s56
	s_nop 0
	global_load_lds_dwordx4 v[232:233], off
	s_mov_b32 m0, s57
	s_nop 0
	global_load_lds_dwordx4 v[234:235], off
	s_waitcnt vmcnt(8)
	s_waitcnt lgkmcnt(0)
	s_setprio 1
	s_barrier
; #define PG8_STAGE(bufoff, gbase, voff) do { _Pragma("unroll") for (int _i = 0; _i < 2; ++_i) \
;         __builtin_amdgcn_global_load_lds((const unsigned*)((const char*)(gbase) + (voff)[_i]), (PG8_LAS unsigned*)(lds + (bufoff) + ldsw + _i * 8192), 16, 0, 0); } while (0)
; #define PG8_LDA(dst, b, h) do { _Pragma("unroll") for (int m = 0; m < 4; ++m) _Pragma("unroll") for (int k = 0; k < 2; ++k) dst[m][k] = *(const PG8_LAS bf16x8*)(lds + PG8_SA(b, h) + aoff + m * 2048 + k * 1024); } while (0)
; #define PG8_LDB(dst, b, h) do { _Pragma("unroll") for (int n = 0; n < 2; ++n) _Pragma("unroll") for (int k = 0; k < 2; ++k) dst[n][k] = *(const PG8_LAS bf16x8*)(lds + PG8_SB(b, h) + boff + n * 2048 + k * 1024); } while (0)
; #define PG8_MMA(ai, bj, At, Bt) do { __builtin_amdgcn_s_setprio(1); _Pragma("unroll") for (int m = 0; m < 4; ++m) _Pragma("unroll") for (int n = 0; n < 2; ++n) _Pragma("unroll") for (int k = 0; k < 2; ++k) \
;         acc[ai][bj][m][n] = __builtin_amdgcn_mfma_f32_16x16x32_bf16(Bt[n][k], At[m][k], acc[ai][bj][m][n], 0, 0, 0); __builtin_amdgcn_s_setprio(0); } while (0)
; #define PG8_WAIT_V(n) asm volatile("s_waitcnt vmcnt(" #n ")" ::: "memory")
; #define PG8_WAIT_L(n) asm volatile("s_waitcnt lgkmcnt(" #n ")" ::: "memory")
; #define PG8_BAR __builtin_amdgcn_s_barrier()
; #define PG8_SCHED __builtin_amdgcn_sched_barrier(0)
; template <class Epi, class Sched, bool ALIGN_EPI = false, bool SP2 = false>
; __device__ __forceinline__ void gemm_phase(PG8_LAS unsigned char* lds, const Gemm g, const Sched& S, const Epi& E) {
;     ...
;             PG8_WAIT_V(8); PG8_WAIT_L(0); PG8_BAR; PG8_MMA(1, 0, At, B0); PG8_MMA(1, 1, At, B1); PG8_BAR; PG8_SCHED;
;             PG8_LDB(B0, 1, 0); PG8_LDB(B1, 1, 1); PG8_SCHED; PG8_LDA(At, 1, 0); PG8_STAGE(PG8_SA(0, 1), a2 + hstep, voffA);
;             PG8_WAIT_V(8); PG8_WAIT_L(0); PG8_BAR; PG8_MMA(0, 0, At, B0); PG8_MMA(0, 1, At, B1); PG8_BAR; PG8_SCHED;
	v_mfma_f32_16x16x32_bf16 v[62:65], v[152:155], v[198:201], v[62:65]
	v_mfma_f32_16x16x32_bf16 v[58:61], v[172:175], v[198:201], v[58:61]
	v_mfma_f32_16x16x32_bf16 v[46:49], v[152:155], v[206:209], v[46:49]
	v_mfma_f32_16x16x32_bf16 v[42:45], v[172:175], v[206:209], v[42:45]
	v_mfma_f32_16x16x32_bf16 v[30:33], v[152:155], v[214:217], v[30:33]
	v_mfma_f32_16x16x32_bf16 v[26:29], v[172:175], v[214:217], v[26:29]
	v_mfma_f32_16x16x32_bf16 v[14:17], v[152:155], v[222:225], v[14:17]
	v_mfma_f32_16x16x32_bf16 v[10:13], v[172:175], v[222:225], v[10:13]
	v_mfma_f32_16x16x32_bf16 v[62:65], v[168:171], v[202:205], v[62:65]
	v_mfma_f32_16x16x32_bf16 v[58:61], v[176:179], v[202:205], v[58:61]
	v_mfma_f32_16x16x32_bf16 v[46:49], v[168:171], v[210:213], v[46:49]
	v_mfma_f32_16x16x32_bf16 v[42:45], v[176:179], v[210:213], v[42:45]
	v_mfma_f32_16x16x32_bf16 v[30:33], v[168:171], v[218:221], v[30:33]
	v_mfma_f32_16x16x32_bf16 v[26:29], v[176:179], v[218:221], v[26:29]
	v_mfma_f32_16x16x32_bf16 v[14:17], v[168:171], v[226:229], v[14:17]
	v_mfma_f32_16x16x32_bf16 v[10:13], v[176:179], v[226:229], v[10:13]
	s_setprio 0
	s_setprio 1
	v_mfma_f32_16x16x32_bf16 v[54:57], v[180:183], v[198:201], v[54:57]
	v_mfma_f32_16x16x32_bf16 v[50:53], v[188:191], v[198:201], v[50:53]
	v_mfma_f32_16x16x32_bf16 v[38:41], v[180:183], v[206:209], v[38:41]
	v_mfma_f32_16x16x32_bf16 v[34:37], v[188:191], v[206:209], v[34:37]
	v_mfma_f32_16x16x32_bf16 v[22:25], v[180:183], v[214:217], v[22:25]
	v_mfma_f32_16x16x32_bf16 v[18:21], v[188:191], v[214:217], v[18:21]
	v_mfma_f32_16x16x32_bf16 v[6:9], v[180:183], v[222:225], v[6:9]
	v_mfma_f32_16x16x32_bf16 v[2:5], v[188:191], v[222:225], v[2:5]
	v_mfma_f32_16x16x32_bf16 v[54:57], v[184:187], v[202:205], v[54:57]
	v_mfma_f32_16x16x32_bf16 v[50:53], v[192:195], v[202:205], v[50:53]
	v_mfma_f32_16x16x32_bf16 v[38:41], v[184:187], v[210:213], v[38:41]
	v_mfma_f32_16x16x32_bf16 v[34:37], v[192:195], v[210:213], v[34:37]
	v_mfma_f32_16x16x32_bf16 v[22:25], v[184:187], v[218:221], v[22:25]
	v_mfma_f32_16x16x32_bf16 v[18:21], v[192:195], v[218:221], v[18:21]
	v_mfma_f32_16x16x32_bf16 v[6:9], v[184:187], v[226:229], v[6:9]
	v_mfma_f32_16x16x32_bf16 v[2:5], v[192:195], v[226:229], v[2:5]
	s_setprio 0
	s_barrier
	s_add_i32 s81, 0, 0x18000
	v_add_u32_e32 v149, s81, v164
	s_add_i32 s82, 0, 0x1c000
	ds_read_b128 v[152:155], v149
	ds_read_b128 v[168:171], v149 offset:1024
	ds_read_b128 v[172:175], v149 offset:2048
	ds_read_b128 v[176:179], v149 offset:3072
	v_add_u32_e32 v149, s82, v164
	ds_read_b128 v[180:183], v149
	ds_read_b128 v[184:187], v149 offset:1024
	ds_read_b128 v[188:191], v149 offset:2048
	ds_read_b128 v[192:195], v149 offset:3072
	s_add_u32 s48, s48, 0x100000
	s_addc_u32 s49, s49, 0
	s_mov_b32 m0, s58
	v_lshl_add_u64 v[236:237], s[48:49], 0, v[130:131]
	ds_read_b128 v[198:201], v161 offset:32768
	ds_read_b128 v[202:205], v161 offset:33792
	ds_read_b128 v[206:209], v161 offset:34816
	ds_read_b128 v[210:213], v161 offset:35840
	ds_read_b128 v[214:217], v161 offset:36864
	ds_read_b128 v[218:221], v161 offset:37888
	ds_read_b128 v[222:225], v161 offset:38912
	ds_read_b128 v[226:229], v161 offset:39936
	global_load_lds_dwordx4 v[236:237], off
	v_lshl_add_u64 v[236:237], s[48:49], 0, v[134:135]
	s_mov_b32 m0, s59
	s_nop 0
	global_load_lds_dwordx4 v[236:237], off
	s_waitcnt vmcnt(8)
	s_waitcnt lgkmcnt(0)
	s_setprio 1
	s_barrier
	v_mfma_f32_16x16x32_bf16 v[126:129], v[152:155], v[198:201], v[126:129]
	v_mfma_f32_16x16x32_bf16 v[122:125], v[172:175], v[198:201], v[122:125]
	v_mfma_f32_16x16x32_bf16 v[110:113], v[152:155], v[206:209], v[110:113]
	v_mfma_f32_16x16x32_bf16 v[106:109], v[172:175], v[206:209], v[106:109]
	v_mfma_f32_16x16x32_bf16 v[94:97], v[152:155], v[214:217], v[94:97]
	v_mfma_f32_16x16x32_bf16 v[90:93], v[172:175], v[214:217], v[90:93]
	v_mfma_f32_16x16x32_bf16 v[78:81], v[152:155], v[222:225], v[78:81]
	v_mfma_f32_16x16x32_bf16 v[74:77], v[172:175], v[222:225], v[74:77]
	v_mfma_f32_16x16x32_bf16 v[126:129], v[168:171], v[202:205], v[126:129]
	v_mfma_f32_16x16x32_bf16 v[122:125], v[176:179], v[202:205], v[122:125]
	v_mfma_f32_16x16x32_bf16 v[110:113], v[168:171], v[210:213], v[110:113]
	v_mfma_f32_16x16x32_bf16 v[106:109], v[176:179], v[210:213], v[106:109]
	v_mfma_f32_16x16x32_bf16 v[94:97], v[168:171], v[218:221], v[94:97]
	v_mfma_f32_16x16x32_bf16 v[90:93], v[176:179], v[218:221], v[90:93]
	v_mfma_f32_16x16x32_bf16 v[78:81], v[168:171], v[226:229], v[78:81]
	v_mfma_f32_16x16x32_bf16 v[74:77], v[176:179], v[226:229], v[74:77]
	s_setprio 0
	s_setprio 1
	v_mfma_f32_16x16x32_bf16 v[118:121], v[180:183], v[198:201], v[118:121]
	v_mfma_f32_16x16x32_bf16 v[114:117], v[188:191], v[198:201], v[114:117]
	v_mfma_f32_16x16x32_bf16 v[102:105], v[180:183], v[206:209], v[102:105]
	v_mfma_f32_16x16x32_bf16 v[98:101], v[188:191], v[206:209], v[98:101]
	v_mfma_f32_16x16x32_bf16 v[86:89], v[180:183], v[214:217], v[86:89]
	v_mfma_f32_16x16x32_bf16 v[82:85], v[188:191], v[214:217], v[82:85]
	v_mfma_f32_16x16x32_bf16 v[70:73], v[180:183], v[222:225], v[70:73]
	v_mfma_f32_16x16x32_bf16 v[66:69], v[188:191], v[222:225], v[66:69]
	v_mfma_f32_16x16x32_bf16 v[118:121], v[184:187], v[202:205], v[118:121]
	v_mfma_f32_16x16x32_bf16 v[114:117], v[192:195], v[202:205], v[114:117]
	v_mfma_f32_16x16x32_bf16 v[102:105], v[184:187], v[210:213], v[102:105]
	v_mfma_f32_16x16x32_bf16 v[98:101], v[192:195], v[210:213], v[98:101]
	v_mfma_f32_16x16x32_bf16 v[86:89], v[184:187], v[218:221], v[86:89]
	v_mfma_f32_16x16x32_bf16 v[82:85], v[192:195], v[218:221], v[82:85]
	v_mfma_f32_16x16x32_bf16 v[70:73], v[184:187], v[226:229], v[70:73]
	v_mfma_f32_16x16x32_bf16 v[66:69], v[192:195], v[226:229], v[66:69]
	s_setprio 0
	s_barrier
; #define PG8_STAGE(bufoff, gbase, voff) do { _Pragma("unroll") for (int _i = 0; _i < 2; ++_i) \
;         __builtin_amdgcn_global_load_lds((const unsigned*)((const char*)(gbase) + (voff)[_i]), (PG8_LAS unsigned*)(lds + (bufoff) + ldsw + _i * 8192), 16, 0, 0); } while (0)
; #define PG8_LDA(dst, b, h) do { _Pragma("unroll") for (int m = 0; m < 4; ++m) _Pragma("unroll") for (int k = 0; k < 2; ++k) dst[m][k] = *(const PG8_LAS bf16x8*)(lds + PG8_SA(b, h) + aoff + m * 2048 + k * 1024); } while (0)
; #define PG8_MMA(ai, bj, At, Bt) do { __builtin_amdgcn_s_setprio(1); _Pragma("unroll") for (int m = 0; m < 4; ++m) _Pragma("unroll") for (int n = 0; n < 2; ++n) _Pragma("unroll") for (int k = 0; k < 2; ++k) \
;         acc[ai][bj][m][n] = __builtin_amdgcn_mfma_f32_16x16x32_bf16(Bt[n][k], At[m][k], acc[ai][bj][m][n], 0, 0, 0); __builtin_amdgcn_s_setprio(0); } while (0)
; #define PG8_WAIT_V(n) asm volatile("s_waitcnt vmcnt(" #n ")" ::: "memory")
; #define PG8_WAIT_L(n) asm volatile("s_waitcnt lgkmcnt(" #n ")" ::: "memory")
; #define PG8_BAR __builtin_amdgcn_s_barrier()
; #define PG8_SCHED __builtin_amdgcn_sched_barrier(0)
; template <class Epi, class Sched, bool ALIGN_EPI = false, bool SP2 = false>
; __device__ __forceinline__ void gemm_phase(PG8_LAS unsigned char* lds, const Gemm g, const Sched& S, const Epi& E) {
;     ...
;             PG8_LDA(At, 1, 1); PG8_STAGE(PG8_SB(1, 0), b3, voffB); PG8_STAGE(PG8_SB(1, 1), b3 + hstep, voffB); PG8_STAGE(PG8_SA(1, 0), a3, voffA);
;             PG8_WAIT_V(8); PG8_WAIT_L(0); PG8_BAR; PG8_MMA(1, 0, At, B0); PG8_MMA(1, 1, At, B1); PG8_BAR; PG8_SCHED;
;     ...
;         if constexpr (ALIGN_EPI) { if (wr == 0) PG8_BAR; }
	s_add_i32 s48, s81, s55
	v_lshl_add_u64 v[156:157], v[156:157], 0, s[10:11]
	s_mov_b32 m0, s48
	ds_read_b128 v[198:201], v161 offset:49152
	ds_read_b128 v[202:205], v161 offset:50176
	ds_read_b128 v[206:209], v161 offset:51200
	ds_read_b128 v[210:213], v161 offset:52224
	ds_read_b128 v[214:217], v161 offset:53248
	ds_read_b128 v[218:221], v161 offset:54272
	ds_read_b128 v[222:225], v161 offset:55296
	ds_read_b128 v[226:229], v161 offset:56320
	global_load_lds_dwordx4 v[156:157], off
	s_add_i32 m0, s48, 0x2000
	s_add_u32 s46, s46, 0x100080
	v_lshl_add_u64 v[156:157], v[230:231], 0, s[10:11]
	s_addc_u32 s47, s47, 0
	s_add_i32 s48, s82, s55
	global_load_lds_dwordx4 v[156:157], off
	v_lshl_add_u64 v[156:157], s[46:47], 0, v[132:133]
	s_mov_b32 m0, s48
	s_nop 0
	global_load_lds_dwordx4 v[156:157], off
	v_lshl_add_u64 v[156:157], s[46:47], 0, v[136:137]
	s_add_i32 m0, s48, 0x2000
	s_nop 0
	global_load_lds_dwordx4 v[156:157], off
	v_lshl_add_u64 v[156:157], v[232:233], 0, s[10:11]
	s_mov_b32 m0, s70
	s_nop 0
	global_load_lds_dwordx4 v[156:157], off
	v_lshl_add_u64 v[156:157], v[234:235], 0, s[10:11]
	s_mov_b32 m0, s71
	s_nop 0
	global_load_lds_dwordx4 v[156:157], off
	s_waitcnt vmcnt(8)
	s_waitcnt lgkmcnt(0)
	s_setprio 1
	s_barrier
	v_mfma_f32_16x16x32_bf16 v[62:65], v[152:155], v[198:201], v[62:65]
	v_mfma_f32_16x16x32_bf16 v[58:61], v[172:175], v[198:201], v[58:61]
	v_mfma_f32_16x16x32_bf16 v[46:49], v[152:155], v[206:209], v[46:49]
	v_mfma_f32_16x16x32_bf16 v[42:45], v[172:175], v[206:209], v[42:45]
	v_mfma_f32_16x16x32_bf16 v[30:33], v[152:155], v[214:217], v[30:33]
	v_mfma_f32_16x16x32_bf16 v[26:29], v[172:175], v[214:217], v[26:29]
	v_mfma_f32_16x16x32_bf16 v[14:17], v[152:155], v[222:225], v[14:17]
	v_mfma_f32_16x16x32_bf16 v[10:13], v[172:175], v[222:225], v[10:13]
	v_mfma_f32_16x16x32_bf16 v[62:65], v[168:171], v[202:205], v[62:65]
	v_mfma_f32_16x16x32_bf16 v[58:61], v[176:179], v[202:205], v[58:61]
	v_mfma_f32_16x16x32_bf16 v[46:49], v[168:171], v[210:213], v[46:49]
	v_mfma_f32_16x16x32_bf16 v[42:45], v[176:179], v[210:213], v[42:45]
	v_mfma_f32_16x16x32_bf16 v[30:33], v[168:171], v[218:221], v[30:33]
	v_mfma_f32_16x16x32_bf16 v[26:29], v[176:179], v[218:221], v[26:29]
	v_mfma_f32_16x16x32_bf16 v[14:17], v[168:171], v[226:229], v[14:17]
	v_mfma_f32_16x16x32_bf16 v[10:13], v[176:179], v[226:229], v[10:13]
	s_setprio 0
	s_setprio 1
	v_mfma_f32_16x16x32_bf16 v[54:57], v[180:183], v[198:201], v[54:57]
	v_mfma_f32_16x16x32_bf16 v[50:53], v[188:191], v[198:201], v[50:53]
	v_mfma_f32_16x16x32_bf16 v[38:41], v[180:183], v[206:209], v[38:41]
	v_mfma_f32_16x16x32_bf16 v[34:37], v[188:191], v[206:209], v[34:37]
	v_mfma_f32_16x16x32_bf16 v[22:25], v[180:183], v[214:217], v[22:25]
	v_mfma_f32_16x16x32_bf16 v[18:21], v[188:191], v[214:217], v[18:21]
	v_mfma_f32_16x16x32_bf16 v[6:9], v[180:183], v[222:225], v[6:9]
	v_mfma_f32_16x16x32_bf16 v[2:5], v[188:191], v[222:225], v[2:5]
	v_mfma_f32_16x16x32_bf16 v[54:57], v[184:187], v[202:205], v[54:57]
	v_mfma_f32_16x16x32_bf16 v[50:53], v[192:195], v[202:205], v[50:53]
	v_mfma_f32_16x16x32_bf16 v[38:41], v[184:187], v[210:213], v[38:41]
	v_mfma_f32_16x16x32_bf16 v[34:37], v[192:195], v[210:213], v[34:37]
	v_mfma_f32_16x16x32_bf16 v[22:25], v[184:187], v[218:221], v[22:25]
	v_mfma_f32_16x16x32_bf16 v[18:21], v[192:195], v[218:221], v[18:21]
	v_mfma_f32_16x16x32_bf16 v[6:9], v[184:187], v[226:229], v[6:9]
	v_mfma_f32_16x16x32_bf16 v[2:5], v[192:195], v[226:229], v[2:5]
	s_setprio 0
	s_barrier
	s_add_i32 s80, s80, 2
	s_add_u32 s44, s44, 0x100
	s_addc_u32 s45, s45, 0
	s_add_u32 s78, s78, 0x100
	s_addc_u32 s79, s79, 0
	s_cmp_gt_u32 s80, 61
	s_cbranch_scc0 .LBB0_217
	s_and_b64 vcc, exec, s[12:13]
	s_cbranch_vccz .LBB0_220
	s_barrier

; #define PG8_STAGE(bufoff, gbase, voff) do { _Pragma("unroll") for (int _i = 0; _i < 2; ++_i) \
;         __builtin_amdgcn_global_load_lds((const unsigned*)((const char*)(gbase) + (voff)[_i]), (PG8_LAS unsigned*)(lds + (bufoff) + ldsw + _i * 8192), 16, 0, 0); } while (0)
; #define PG8_LDA(dst, b, h) do { _Pragma("unroll") for (int m = 0; m < 4; ++m) _Pragma("unroll") for (int k = 0; k < 2; ++k) dst[m][k] = *(const PG8_LAS bf16x8*)(lds + PG8_SA(b, h) + aoff + m * 2048 + k * 1024); } while (0)
; #define PG8_LDB(dst, b, h) do { _Pragma("unroll") for (int n = 0; n < 2; ++n) _Pragma("unroll") for (int k = 0; k < 2; ++k) dst[n][k] = *(const PG8_LAS bf16x8*)(lds + PG8_SB(b, h) + boff + n * 2048 + k * 1024); } while (0)
; #define PG8_MMA(ai, bj, At, Bt) do { __builtin_amdgcn_s_setprio(1); _Pragma("unroll") for (int m = 0; m < 4; ++m) _Pragma("unroll") for (int n = 0; n < 2; ++n) _Pragma("unroll") for (int k = 0; k < 2; ++k) \
;         acc[ai][bj][m][n] = __builtin_amdgcn_mfma_f32_16x16x32_bf16(Bt[n][k], At[m][k], acc[ai][bj][m][n], 0, 0, 0); __builtin_amdgcn_s_setprio(0); } while (0)
; #define PG8_WAIT_V(n) asm volatile("s_waitcnt vmcnt(" #n ")" ::: "memory")
; #define PG8_WAIT_L(n) asm volatile("s_waitcnt lgkmcnt(" #n ")" ::: "memory")
; template <class Epi, class Sched, bool ALIGN_EPI = false, bool SP2 = false>
; __device__ __forceinline__ void gemm_phase(PG8_LAS unsigned char* lds, const Gemm g, const Sched& S, const Epi& E) {
;     ...
;             const bool last = (t == nt - 2);
;             const char* a1 = cA + (size_t)(t + 1) * kstep;
;             const char* a2 = last ? nA : cA + (size_t)(t + 2) * kstep; const char* b2 = last ? nB : cB + (size_t)(t + 2) * kstep;
;             const char* a3 = a2 + kstep; const char* b3 = b2 + kstep;
;             if (last && has_next) S.a_ready(nxt);
;             if constexpr (SP2) {
;             PG8_LDB(B0, 0, 0); PG8_LDB(B1, 0, 1); PG8_SCHED; PG8_LDA(At, 0, 0); PG8_STAGE(PG8_SA(1, 1), a1 + hstep, voffA);
;             PG8_WAIT_V(8); PG8_WAIT_L(0); PG8_BAR; PG8_MMA(0, 0, At, B0); PG8_MMA(0, 1, At, B1); PG8_BAR; PG8_SCHED;
;             PG8_LDA(At, 0, 1); PG8_STAGE(PG8_SB(0, 0), b2, voffB); PG8_STAGE(PG8_SB(0, 1), b2 + hstep, voffB); PG8_STAGE(PG8_SA(0, 0), a2, voffA);
;             PG8_WAIT_V(8); PG8_WAIT_L(0); PG8_BAR; PG8_MMA(1, 0, At, B0); PG8_MMA(1, 1, At, B1); PG8_BAR; PG8_SCHED;
.LBB0_710:
	ds_read_b128 v[146:149], v160
	ds_read_b128 v[164:167], v160 offset:1024
	ds_read_b128 v[168:171], v160 offset:2048
	ds_read_b128 v[172:175], v160 offset:3072
	ds_read_b128 v[176:179], v161
	ds_read_b128 v[180:183], v161 offset:1024
	ds_read_b128 v[184:187], v161 offset:2048
	ds_read_b128 v[188:191], v161 offset:3072
	s_add_u32 s50, s48, 0xfff00080
	s_addc_u32 s51, s49, -1
	s_cmp_eq_u32 s76, 60
	s_cselect_b32 s53, s43, s51
	s_cselect_b32 s52, s72, s50
	s_cselect_b32 s51, s41, s75
	s_cselect_b32 s50, s73, s74
	v_lshl_add_u64 v[226:227], s[48:49], 0, v[138:139]
	s_add_i32 m0, s9, 0xc000
	ds_read_b128 v[192:195], v162
	ds_read_b128 v[198:201], v162 offset:1024
	ds_read_b128 v[202:205], v162 offset:2048
	ds_read_b128 v[206:209], v162 offset:3072
	ds_read_b128 v[210:213], v162 offset:4096
	ds_read_b128 v[214:217], v162 offset:5120
	ds_read_b128 v[218:221], v162 offset:6144
	ds_read_b128 v[222:225], v162 offset:7168
	global_load_lds_dwordx4 v[226:227], off
	v_lshl_add_u64 v[226:227], s[48:49], 0, v[140:141]
	s_add_i32 m0, s9, 0xe000
	s_nop 0
	global_load_lds_dwordx4 v[226:227], off
	s_waitcnt vmcnt(8)
	s_waitcnt lgkmcnt(0)
	s_setprio 1
	s_barrier
	v_mfma_f32_16x16x32_bf16 v[126:129], v[146:149], v[192:195], v[126:129]
	v_mfma_f32_16x16x32_bf16 v[122:125], v[168:171], v[192:195], v[122:125]
	v_mfma_f32_16x16x32_bf16 v[110:113], v[146:149], v[202:205], v[110:113]
	v_mfma_f32_16x16x32_bf16 v[106:109], v[168:171], v[202:205], v[106:109]
	v_mfma_f32_16x16x32_bf16 v[94:97], v[146:149], v[210:213], v[94:97]
	v_mfma_f32_16x16x32_bf16 v[90:93], v[168:171], v[210:213], v[90:93]
	v_mfma_f32_16x16x32_bf16 v[78:81], v[146:149], v[218:221], v[78:81]
	v_mfma_f32_16x16x32_bf16 v[74:77], v[168:171], v[218:221], v[74:77]
	v_mfma_f32_16x16x32_bf16 v[126:129], v[164:167], v[198:201], v[126:129]
	v_mfma_f32_16x16x32_bf16 v[122:125], v[172:175], v[198:201], v[122:125]
	v_mfma_f32_16x16x32_bf16 v[110:113], v[164:167], v[206:209], v[110:113]
	v_mfma_f32_16x16x32_bf16 v[106:109], v[172:175], v[206:209], v[106:109]
	v_mfma_f32_16x16x32_bf16 v[94:97], v[164:167], v[214:217], v[94:97]
	v_mfma_f32_16x16x32_bf16 v[90:93], v[172:175], v[214:217], v[90:93]
	v_mfma_f32_16x16x32_bf16 v[78:81], v[164:167], v[222:225], v[78:81]
	v_mfma_f32_16x16x32_bf16 v[74:77], v[172:175], v[222:225], v[74:77]
	s_setprio 0
	s_setprio 1
	v_mfma_f32_16x16x32_bf16 v[118:121], v[176:179], v[192:195], v[118:121]
	v_mfma_f32_16x16x32_bf16 v[114:117], v[184:187], v[192:195], v[114:117]
	v_mfma_f32_16x16x32_bf16 v[102:105], v[176:179], v[202:205], v[102:105]
	v_mfma_f32_16x16x32_bf16 v[98:101], v[184:187], v[202:205], v[98:101]
	v_mfma_f32_16x16x32_bf16 v[86:89], v[176:179], v[210:213], v[86:89]
	v_mfma_f32_16x16x32_bf16 v[82:85], v[184:187], v[210:213], v[82:85]
	v_mfma_f32_16x16x32_bf16 v[70:73], v[176:179], v[218:221], v[70:73]
	v_mfma_f32_16x16x32_bf16 v[66:69], v[184:187], v[218:221], v[66:69]
	v_mfma_f32_16x16x32_bf16 v[118:121], v[180:183], v[198:201], v[118:121]
	v_mfma_f32_16x16x32_bf16 v[114:117], v[188:191], v[198:201], v[114:117]
	v_mfma_f32_16x16x32_bf16 v[102:105], v[180:183], v[206:209], v[102:105]
	v_mfma_f32_16x16x32_bf16 v[98:101], v[188:191], v[206:209], v[98:101]
	v_mfma_f32_16x16x32_bf16 v[86:89], v[180:183], v[214:217], v[86:89]
	v_mfma_f32_16x16x32_bf16 v[82:85], v[188:191], v[214:217], v[82:85]
	v_mfma_f32_16x16x32_bf16 v[70:73], v[180:183], v[222:225], v[70:73]
	v_mfma_f32_16x16x32_bf16 v[66:69], v[188:191], v[222:225], v[66:69]
	s_setprio 0
	s_barrier
	s_add_i32 s77, s69, s56
	v_lshl_add_u64 v[226:227], s[50:51], 0, v[132:133]
	s_mov_b32 m0, s77
	ds_read_b128 v[192:195], v162 offset:16384
	ds_read_b128 v[198:201], v162 offset:17408
	ds_read_b128 v[202:205], v162 offset:18432
	ds_read_b128 v[206:209], v162 offset:19456
	ds_read_b128 v[210:213], v162 offset:20480
	ds_read_b128 v[214:217], v162 offset:21504
	ds_read_b128 v[218:221], v162 offset:22528
	ds_read_b128 v[222:225], v162 offset:23552
	global_load_lds_dwordx4 v[226:227], off
	s_add_i32 m0, s77, 0x2000
	s_add_u32 s78, s50, 0x100000
	v_lshl_add_u64 v[228:229], s[50:51], 0, v[136:137]
	s_addc_u32 s79, s51, 0
	s_add_i32 s77, s70, s56
	global_load_lds_dwordx4 v[228:229], off
	v_lshl_add_u64 v[230:231], s[78:79], 0, v[132:133]
	s_mov_b32 m0, s77
	v_lshl_add_u64 v[232:233], s[52:53], 0, v[134:135]
	global_load_lds_dwordx4 v[230:231], off
	v_lshl_add_u64 v[230:231], s[78:79], 0, v[136:137]
	s_add_i32 m0, s77, 0x2000
	s_nop 0
	global_load_lds_dwordx4 v[230:231], off
	v_lshl_add_u64 v[230:231], s[52:53], 0, v[130:131]
	s_mov_b32 m0, s9
	s_nop 0
	global_load_lds_dwordx4 v[230:231], off
	s_mov_b32 m0, s57
	s_nop 0
	global_load_lds_dwordx4 v[232:233], off
	s_waitcnt vmcnt(8)
	s_waitcnt lgkmcnt(0)
	s_setprio 1
	s_barrier
; #define PG8_STAGE(bufoff, gbase, voff) do { _Pragma("unroll") for (int _i = 0; _i < 2; ++_i) \
;         __builtin_amdgcn_global_load_lds((const unsigned*)((const char*)(gbase) + (voff)[_i]), (PG8_LAS unsigned*)(lds + (bufoff) + ldsw + _i * 8192), 16, 0, 0); } while (0)
; #define PG8_LDA(dst, b, h) do { _Pragma("unroll") for (int m = 0; m < 4; ++m) _Pragma("unroll") for (int k = 0; k < 2; ++k) dst[m][k] = *(const PG8_LAS bf16x8*)(lds + PG8_SA(b, h) + aoff + m * 2048 + k * 1024); } while (0)
; #define PG8_LDB(dst, b, h) do { _Pragma("unroll") for (int n = 0; n < 2; ++n) _Pragma("unroll") for (int k = 0; k < 2; ++k) dst[n][k] = *(const PG8_LAS bf16x8*)(lds + PG8_SB(b, h) + boff + n * 2048 + k * 1024); } while (0)
; #define PG8_MMA(ai, bj, At, Bt) do { __builtin_amdgcn_s_setprio(1); _Pragma("unroll") for (int m = 0; m < 4; ++m) _Pragma("unroll") for (int n = 0; n < 2; ++n) _Pragma("unroll") for (int k = 0; k < 2; ++k) \
;         acc[ai][bj][m][n] = __builtin_amdgcn_mfma_f32_16x16x32_bf16(Bt[n][k], At[m][k], acc[ai][bj][m][n], 0, 0, 0); __builtin_amdgcn_s_setprio(0); } while (0)
; #define PG8_WAIT_V(n) asm volatile("s_waitcnt vmcnt(" #n ")" ::: "memory")
; #define PG8_WAIT_L(n) asm volatile("s_waitcnt lgkmcnt(" #n ")" ::: "memory")
; #define PG8_BAR __builtin_amdgcn_s_barrier()
; #define PG8_SCHED __builtin_amdgcn_sched_barrier(0)
; template <class Epi, class Sched, bool ALIGN_EPI = false, bool SP2 = false>
; __device__ __forceinline__ void gemm_phase(PG8_LAS unsigned char* lds, const Gemm g, const Sched& S, const Epi& E) {
;     ...
;             PG8_WAIT_V(8); PG8_WAIT_L(0); PG8_BAR; PG8_MMA(1, 0, At, B0); PG8_MMA(1, 1, At, B1); PG8_BAR; PG8_SCHED;
;             PG8_LDB(B0, 1, 0); PG8_LDB(B1, 1, 1); PG8_SCHED; PG8_LDA(At, 1, 0); PG8_STAGE(PG8_SA(0, 1), a2 + hstep, voffA);
;             PG8_WAIT_V(8); PG8_WAIT_L(0); PG8_BAR; PG8_MMA(0, 0, At, B0); PG8_MMA(0, 1, At, B1); PG8_BAR; PG8_SCHED;
	v_mfma_f32_16x16x32_bf16 v[62:65], v[146:149], v[192:195], v[62:65]
	v_mfma_f32_16x16x32_bf16 v[58:61], v[168:171], v[192:195], v[58:61]
	v_mfma_f32_16x16x32_bf16 v[46:49], v[146:149], v[202:205], v[46:49]
	v_mfma_f32_16x16x32_bf16 v[42:45], v[168:171], v[202:205], v[42:45]
	v_mfma_f32_16x16x32_bf16 v[30:33], v[146:149], v[210:213], v[30:33]
	v_mfma_f32_16x16x32_bf16 v[26:29], v[168:171], v[210:213], v[26:29]
	v_mfma_f32_16x16x32_bf16 v[14:17], v[146:149], v[218:221], v[14:17]
	v_mfma_f32_16x16x32_bf16 v[10:13], v[168:171], v[218:221], v[10:13]
	v_mfma_f32_16x16x32_bf16 v[62:65], v[164:167], v[198:201], v[62:65]
	v_mfma_f32_16x16x32_bf16 v[58:61], v[172:175], v[198:201], v[58:61]
	v_mfma_f32_16x16x32_bf16 v[46:49], v[164:167], v[206:209], v[46:49]
	v_mfma_f32_16x16x32_bf16 v[42:45], v[172:175], v[206:209], v[42:45]
	v_mfma_f32_16x16x32_bf16 v[30:33], v[164:167], v[214:217], v[30:33]
	v_mfma_f32_16x16x32_bf16 v[26:29], v[172:175], v[214:217], v[26:29]
	v_mfma_f32_16x16x32_bf16 v[14:17], v[164:167], v[222:225], v[14:17]
	v_mfma_f32_16x16x32_bf16 v[10:13], v[172:175], v[222:225], v[10:13]
	s_setprio 0
	s_setprio 1
	v_mfma_f32_16x16x32_bf16 v[54:57], v[176:179], v[192:195], v[54:57]
	v_mfma_f32_16x16x32_bf16 v[50:53], v[184:187], v[192:195], v[50:53]
	v_mfma_f32_16x16x32_bf16 v[38:41], v[176:179], v[202:205], v[38:41]
	v_mfma_f32_16x16x32_bf16 v[34:37], v[184:187], v[202:205], v[34:37]
	v_mfma_f32_16x16x32_bf16 v[22:25], v[176:179], v[210:213], v[22:25]
	v_mfma_f32_16x16x32_bf16 v[18:21], v[184:187], v[210:213], v[18:21]
	v_mfma_f32_16x16x32_bf16 v[6:9], v[176:179], v[218:221], v[6:9]
	v_mfma_f32_16x16x32_bf16 v[2:5], v[184:187], v[218:221], v[2:5]
	v_mfma_f32_16x16x32_bf16 v[54:57], v[180:183], v[198:201], v[54:57]
	v_mfma_f32_16x16x32_bf16 v[50:53], v[188:191], v[198:201], v[50:53]
	v_mfma_f32_16x16x32_bf16 v[38:41], v[180:183], v[206:209], v[38:41]
	v_mfma_f32_16x16x32_bf16 v[34:37], v[188:191], v[206:209], v[34:37]
	v_mfma_f32_16x16x32_bf16 v[22:25], v[180:183], v[214:217], v[22:25]
	v_mfma_f32_16x16x32_bf16 v[18:21], v[188:191], v[214:217], v[18:21]
	v_mfma_f32_16x16x32_bf16 v[6:9], v[180:183], v[222:225], v[6:9]
	v_mfma_f32_16x16x32_bf16 v[2:5], v[188:191], v[222:225], v[2:5]
	s_setprio 0
	s_barrier
	s_add_i32 s77, 0, 0x18000
	s_add_i32 s78, 0, 0x1c000
	v_add_u32_e32 v172, s77, v151
	v_add_u32_e32 v188, s78, v151
	ds_read_b128 v[146:149], v172
	ds_read_b128 v[164:167], v172 offset:1024
	ds_read_b128 v[168:171], v172 offset:2048
	ds_read_b128 v[172:175], v172 offset:3072
	ds_read_b128 v[176:179], v188
	ds_read_b128 v[180:183], v188 offset:1024
	ds_read_b128 v[184:187], v188 offset:2048
	ds_read_b128 v[188:191], v188 offset:3072
	s_add_u32 s52, s52, 0x100000
	s_addc_u32 s53, s53, 0
	s_mov_b32 m0, s58
	v_lshl_add_u64 v[234:235], s[52:53], 0, v[130:131]
	ds_read_b128 v[192:195], v162 offset:32768
	ds_read_b128 v[198:201], v162 offset:33792
	ds_read_b128 v[202:205], v162 offset:34816
	ds_read_b128 v[206:209], v162 offset:35840
	ds_read_b128 v[210:213], v162 offset:36864
	ds_read_b128 v[214:217], v162 offset:37888
	ds_read_b128 v[218:221], v162 offset:38912
	ds_read_b128 v[222:225], v162 offset:39936
	global_load_lds_dwordx4 v[234:235], off
	v_lshl_add_u64 v[234:235], s[52:53], 0, v[134:135]
	s_mov_b32 m0, s59
	s_nop 0
	global_load_lds_dwordx4 v[234:235], off
	s_waitcnt vmcnt(8)
	s_waitcnt lgkmcnt(0)
	s_setprio 1
	s_barrier
	v_mfma_f32_16x16x32_bf16 v[126:129], v[146:149], v[192:195], v[126:129]
	v_mfma_f32_16x16x32_bf16 v[122:125], v[168:171], v[192:195], v[122:125]
	v_mfma_f32_16x16x32_bf16 v[110:113], v[146:149], v[202:205], v[110:113]
	v_mfma_f32_16x16x32_bf16 v[106:109], v[168:171], v[202:205], v[106:109]
	v_mfma_f32_16x16x32_bf16 v[94:97], v[146:149], v[210:213], v[94:97]
	v_mfma_f32_16x16x32_bf16 v[90:93], v[168:171], v[210:213], v[90:93]
	v_mfma_f32_16x16x32_bf16 v[78:81], v[146:149], v[218:221], v[78:81]
	v_mfma_f32_16x16x32_bf16 v[74:77], v[168:171], v[218:221], v[74:77]
	v_mfma_f32_16x16x32_bf16 v[126:129], v[164:167], v[198:201], v[126:129]
	v_mfma_f32_16x16x32_bf16 v[122:125], v[172:175], v[198:201], v[122:125]
	v_mfma_f32_16x16x32_bf16 v[110:113], v[164:167], v[206:209], v[110:113]
	v_mfma_f32_16x16x32_bf16 v[106:109], v[172:175], v[206:209], v[106:109]
	v_mfma_f32_16x16x32_bf16 v[94:97], v[164:167], v[214:217], v[94:97]
	v_mfma_f32_16x16x32_bf16 v[90:93], v[172:175], v[214:217], v[90:93]
	v_mfma_f32_16x16x32_bf16 v[78:81], v[164:167], v[222:225], v[78:81]
	v_mfma_f32_16x16x32_bf16 v[74:77], v[172:175], v[222:225], v[74:77]
	s_setprio 0
	s_setprio 1
	v_mfma_f32_16x16x32_bf16 v[118:121], v[176:179], v[192:195], v[118:121]
	v_mfma_f32_16x16x32_bf16 v[114:117], v[184:187], v[192:195], v[114:117]
	v_mfma_f32_16x16x32_bf16 v[102:105], v[176:179], v[202:205], v[102:105]
	v_mfma_f32_16x16x32_bf16 v[98:101], v[184:187], v[202:205], v[98:101]
	v_mfma_f32_16x16x32_bf16 v[86:89], v[176:179], v[210:213], v[86:89]
	v_mfma_f32_16x16x32_bf16 v[82:85], v[184:187], v[210:213], v[82:85]
	v_mfma_f32_16x16x32_bf16 v[70:73], v[176:179], v[218:221], v[70:73]
	v_mfma_f32_16x16x32_bf16 v[66:69], v[184:187], v[218:221], v[66:69]
	v_mfma_f32_16x16x32_bf16 v[118:121], v[180:183], v[198:201], v[118:121]
	v_mfma_f32_16x16x32_bf16 v[114:117], v[188:191], v[198:201], v[114:117]
	v_mfma_f32_16x16x32_bf16 v[102:105], v[180:183], v[206:209], v[102:105]
	v_mfma_f32_16x16x32_bf16 v[98:101], v[188:191], v[206:209], v[98:101]
	v_mfma_f32_16x16x32_bf16 v[86:89], v[180:183], v[214:217], v[86:89]
	v_mfma_f32_16x16x32_bf16 v[82:85], v[188:191], v[214:217], v[82:85]
	v_mfma_f32_16x16x32_bf16 v[70:73], v[180:183], v[222:225], v[70:73]
	v_mfma_f32_16x16x32_bf16 v[66:69], v[188:191], v[222:225], v[66:69]
	s_setprio 0
	s_barrier
; #define PG8_STAGE(bufoff, gbase, voff) do { _Pragma("unroll") for (int _i = 0; _i < 2; ++_i) \
;         __builtin_amdgcn_global_load_lds((const unsigned*)((const char*)(gbase) + (voff)[_i]), (PG8_LAS unsigned*)(lds + (bufoff) + ldsw + _i * 8192), 16, 0, 0); } while (0)
; #define PG8_LDA(dst, b, h) do { _Pragma("unroll") for (int m = 0; m < 4; ++m) _Pragma("unroll") for (int k = 0; k < 2; ++k) dst[m][k] = *(const PG8_LAS bf16x8*)(lds + PG8_SA(b, h) + aoff + m * 2048 + k * 1024); } while (0)
; #define PG8_MMA(ai, bj, At, Bt) do { __builtin_amdgcn_s_setprio(1); _Pragma("unroll") for (int m = 0; m < 4; ++m) _Pragma("unroll") for (int n = 0; n < 2; ++n) _Pragma("unroll") for (int k = 0; k < 2; ++k) \
;         acc[ai][bj][m][n] = __builtin_amdgcn_mfma_f32_16x16x32_bf16(Bt[n][k], At[m][k], acc[ai][bj][m][n], 0, 0, 0); __builtin_amdgcn_s_setprio(0); } while (0)
; #define PG8_WAIT_V(n) asm volatile("s_waitcnt vmcnt(" #n ")" ::: "memory")
; #define PG8_WAIT_L(n) asm volatile("s_waitcnt lgkmcnt(" #n ")" ::: "memory")
; #define PG8_BAR __builtin_amdgcn_s_barrier()
; #define PG8_SCHED __builtin_amdgcn_sched_barrier(0)
; template <class Epi, class Sched, bool ALIGN_EPI = false, bool SP2 = false>
; __device__ __forceinline__ void gemm_phase(PG8_LAS unsigned char* lds, const Gemm g, const Sched& S, const Epi& E) {
;     ...
;             PG8_LDA(At, 1, 1); PG8_STAGE(PG8_SB(1, 0), b3, voffB); PG8_STAGE(PG8_SB(1, 1), b3 + hstep, voffB); PG8_STAGE(PG8_SA(1, 0), a3, voffA);
;             PG8_WAIT_V(8); PG8_WAIT_L(0); PG8_BAR; PG8_MMA(1, 0, At, B0); PG8_MMA(1, 1, At, B1); PG8_BAR; PG8_SCHED;
;     ...
;         if constexpr (ALIGN_EPI) { if (wr == 0) PG8_BAR; }
	s_add_i32 s52, s77, s56
	v_lshl_add_u64 v[226:227], v[226:227], 0, s[36:37]
	s_mov_b32 m0, s52
	ds_read_b128 v[192:195], v162 offset:49152
	ds_read_b128 v[198:201], v162 offset:50176
	ds_read_b128 v[202:205], v162 offset:51200
	ds_read_b128 v[206:209], v162 offset:52224
	ds_read_b128 v[210:213], v162 offset:53248
	ds_read_b128 v[214:217], v162 offset:54272
	ds_read_b128 v[218:221], v162 offset:55296
	ds_read_b128 v[222:225], v162 offset:56320
	global_load_lds_dwordx4 v[226:227], off
	s_add_i32 m0, s52, 0x2000
	s_add_u32 s50, s50, 0x100080
	v_lshl_add_u64 v[226:227], v[228:229], 0, s[36:37]
	s_addc_u32 s51, s51, 0
	s_add_i32 s52, s78, s56
	global_load_lds_dwordx4 v[226:227], off
	v_lshl_add_u64 v[226:227], s[50:51], 0, v[132:133]
	s_mov_b32 m0, s52
	s_nop 0
	global_load_lds_dwordx4 v[226:227], off
	v_lshl_add_u64 v[226:227], s[50:51], 0, v[136:137]
	s_add_i32 m0, s52, 0x2000
	s_nop 0
	global_load_lds_dwordx4 v[226:227], off
	v_lshl_add_u64 v[226:227], v[230:231], 0, s[36:37]
	s_mov_b32 m0, s61
	s_nop 0
	global_load_lds_dwordx4 v[226:227], off
	v_lshl_add_u64 v[226:227], v[232:233], 0, s[36:37]
	s_mov_b32 m0, s62
	s_nop 0
	global_load_lds_dwordx4 v[226:227], off
	s_waitcnt vmcnt(8)
	s_waitcnt lgkmcnt(0)
	s_setprio 1
	s_barrier
	v_mfma_f32_16x16x32_bf16 v[62:65], v[146:149], v[192:195], v[62:65]
	v_mfma_f32_16x16x32_bf16 v[58:61], v[168:171], v[192:195], v[58:61]
	v_mfma_f32_16x16x32_bf16 v[46:49], v[146:149], v[202:205], v[46:49]
	v_mfma_f32_16x16x32_bf16 v[42:45], v[168:171], v[202:205], v[42:45]
	v_mfma_f32_16x16x32_bf16 v[30:33], v[146:149], v[210:213], v[30:33]
	v_mfma_f32_16x16x32_bf16 v[26:29], v[168:171], v[210:213], v[26:29]
	v_mfma_f32_16x16x32_bf16 v[14:17], v[146:149], v[218:221], v[14:17]
	v_mfma_f32_16x16x32_bf16 v[10:13], v[168:171], v[218:221], v[10:13]
	v_mfma_f32_16x16x32_bf16 v[62:65], v[164:167], v[198:201], v[62:65]
	v_mfma_f32_16x16x32_bf16 v[58:61], v[172:175], v[198:201], v[58:61]
	v_mfma_f32_16x16x32_bf16 v[46:49], v[164:167], v[206:209], v[46:49]
	v_mfma_f32_16x16x32_bf16 v[42:45], v[172:175], v[206:209], v[42:45]
	v_mfma_f32_16x16x32_bf16 v[30:33], v[164:167], v[214:217], v[30:33]
	v_mfma_f32_16x16x32_bf16 v[26:29], v[172:175], v[214:217], v[26:29]
	v_mfma_f32_16x16x32_bf16 v[14:17], v[164:167], v[222:225], v[14:17]
	v_mfma_f32_16x16x32_bf16 v[10:13], v[172:175], v[222:225], v[10:13]
	s_setprio 0
	s_setprio 1
	v_mfma_f32_16x16x32_bf16 v[54:57], v[176:179], v[192:195], v[54:57]
	v_mfma_f32_16x16x32_bf16 v[50:53], v[184:187], v[192:195], v[50:53]
	v_mfma_f32_16x16x32_bf16 v[38:41], v[176:179], v[202:205], v[38:41]
	v_mfma_f32_16x16x32_bf16 v[34:37], v[184:187], v[202:205], v[34:37]
	v_mfma_f32_16x16x32_bf16 v[22:25], v[176:179], v[210:213], v[22:25]
	v_mfma_f32_16x16x32_bf16 v[18:21], v[184:187], v[210:213], v[18:21]
	v_mfma_f32_16x16x32_bf16 v[6:9], v[176:179], v[218:221], v[6:9]
	v_mfma_f32_16x16x32_bf16 v[2:5], v[184:187], v[218:221], v[2:5]
	v_mfma_f32_16x16x32_bf16 v[54:57], v[180:183], v[198:201], v[54:57]
	v_mfma_f32_16x16x32_bf16 v[50:53], v[188:191], v[198:201], v[50:53]
	v_mfma_f32_16x16x32_bf16 v[38:41], v[180:183], v[206:209], v[38:41]
	v_mfma_f32_16x16x32_bf16 v[34:37], v[188:191], v[206:209], v[34:37]
	v_mfma_f32_16x16x32_bf16 v[22:25], v[180:183], v[214:217], v[22:25]
	v_mfma_f32_16x16x32_bf16 v[18:21], v[188:191], v[214:217], v[18:21]
	v_mfma_f32_16x16x32_bf16 v[6:9], v[180:183], v[222:225], v[6:9]
	v_mfma_f32_16x16x32_bf16 v[2:5], v[188:191], v[222:225], v[2:5]
	s_setprio 0
	s_barrier
	s_add_i32 s76, s76, 2
	s_add_u32 s48, s48, 0x100
	s_addc_u32 s49, s49, 0
	s_add_u32 s74, s74, 0x100
	s_addc_u32 s75, s75, 0
	s_cmp_gt_u32 s76, 61
	s_cbranch_scc0 .LBB0_710
	s_and_b64 vcc, exec, s[38:39]
	s_cbranch_vccz .LBB0_713
	s_barrier

; #define PG8_STAGE(bufoff, gbase, voff) do { _Pragma("unroll") for (int _i = 0; _i < 2; ++_i) \
;         __builtin_amdgcn_global_load_lds((const unsigned*)((const char*)(gbase) + (voff)[_i]), (PG8_LAS unsigned*)(lds + (bufoff) + ldsw + _i * 8192), 16, 0, 0); } while (0)
; #define PG8_LDA(dst, b, h) do { _Pragma("unroll") for (int m = 0; m < 4; ++m) _Pragma("unroll") for (int k = 0; k < 2; ++k) dst[m][k] = *(const PG8_LAS bf16x8*)(lds + PG8_SA(b, h) + aoff + m * 2048 + k * 1024); } while (0)
; #define PG8_LDB(dst, b, h) do { _Pragma("unroll") for (int n = 0; n < 2; ++n) _Pragma("unroll") for (int k = 0; k < 2; ++k) dst[n][k] = *(const PG8_LAS bf16x8*)(lds + PG8_SB(b, h) + boff + n * 2048 + k * 1024); } while (0)
; #define PG8_MMA(ai, bj, At, Bt) do { __builtin_amdgcn_s_setprio(1); _Pragma("unroll") for (int m = 0; m < 4; ++m) _Pragma("unroll") for (int n = 0; n < 2; ++n) _Pragma("unroll") for (int k = 0; k < 2; ++k) \
;         acc[ai][bj][m][n] = __builtin_amdgcn_mfma_f32_16x16x32_bf16(Bt[n][k], At[m][k], acc[ai][bj][m][n], 0, 0, 0); __builtin_amdgcn_s_setprio(0); } while (0)
; #define PG8_WAIT_V(n) asm volatile("s_waitcnt vmcnt(" #n ")" ::: "memory")
; #define PG8_WAIT_L(n) asm volatile("s_waitcnt lgkmcnt(" #n ")" ::: "memory")
; template <class Epi, class Sched, bool ALIGN_EPI = false, bool SP2 = false>
; __device__ __forceinline__ void gemm_phase(PG8_LAS unsigned char* lds, const Gemm g, const Sched& S, const Epi& E) {
;     ...
;             const bool last = (t == nt - 2);
;             const char* a1 = cA + (size_t)(t + 1) * kstep;
;             const char* a2 = last ? nA : cA + (size_t)(t + 2) * kstep; const char* b2 = last ? nB : cB + (size_t)(t + 2) * kstep;
;             const char* a3 = a2 + kstep; const char* b3 = b2 + kstep;
;             if (last && has_next) S.a_ready(nxt);
;             if constexpr (SP2) {
;             PG8_LDB(B0, 0, 0); PG8_LDB(B1, 0, 1); PG8_SCHED; PG8_LDA(At, 0, 0); PG8_STAGE(PG8_SA(1, 1), a1 + hstep, voffA);
;             PG8_WAIT_V(8); PG8_WAIT_L(0); PG8_BAR; PG8_MMA(0, 0, At, B0); PG8_MMA(0, 1, At, B1); PG8_BAR; PG8_SCHED;
;             PG8_LDA(At, 0, 1); PG8_STAGE(PG8_SB(0, 0), b2, voffB); PG8_STAGE(PG8_SB(0, 1), b2 + hstep, voffB); PG8_STAGE(PG8_SA(0, 0), a2, voffA);
;             PG8_WAIT_V(8); PG8_WAIT_L(0); PG8_BAR; PG8_MMA(1, 0, At, B0); PG8_MMA(1, 1, At, B1); PG8_BAR; PG8_SCHED;
.LBB0_881:
	ds_read_b128 v[156:159], v152
	ds_read_b128 v[160:163], v152 offset:1024
	ds_read_b128 v[164:167], v152 offset:2048
	ds_read_b128 v[168:171], v152 offset:3072
	ds_read_b128 v[172:175], v153
	ds_read_b128 v[176:179], v153 offset:1024
	ds_read_b128 v[180:183], v153 offset:2048
	ds_read_b128 v[184:187], v153 offset:3072
	s_add_u32 s46, s44, 0xfff00080
	s_addc_u32 s47, s45, -1
	s_cmp_eq_u32 s74, 60
	s_cselect_b32 s49, s37, s47
	s_cselect_b32 s48, s70, s46
	s_cselect_b32 s47, s35, s73
	s_cselect_b32 s46, s71, s72
	v_lshl_add_u64 v[146:147], s[44:45], 0, v[138:139]
	s_add_i32 m0, s43, 0xc000
	ds_read_b128 v[188:191], v154
	ds_read_b128 v[192:195], v154 offset:1024
	ds_read_b128 v[198:201], v154 offset:2048
	ds_read_b128 v[202:205], v154 offset:3072
	ds_read_b128 v[206:209], v154 offset:4096
	ds_read_b128 v[210:213], v154 offset:5120
	ds_read_b128 v[214:217], v154 offset:6144
	ds_read_b128 v[218:221], v154 offset:7168
	global_load_lds_dwordx4 v[146:147], off
	v_lshl_add_u64 v[146:147], s[44:45], 0, v[140:141]
	s_add_i32 m0, s43, 0xe000
	s_nop 0
	global_load_lds_dwordx4 v[146:147], off
	s_waitcnt vmcnt(8)
	s_waitcnt lgkmcnt(0)
	s_setprio 1
	s_barrier
	v_mfma_f32_16x16x32_bf16 v[122:125], v[156:159], v[188:191], v[122:125]
	v_mfma_f32_16x16x32_bf16 v[114:117], v[164:167], v[188:191], v[114:117]
	v_mfma_f32_16x16x32_bf16 v[106:109], v[156:159], v[198:201], v[106:109]
	v_mfma_f32_16x16x32_bf16 v[98:101], v[164:167], v[198:201], v[98:101]
	v_mfma_f32_16x16x32_bf16 v[90:93], v[156:159], v[206:209], v[90:93]
	v_mfma_f32_16x16x32_bf16 v[82:85], v[164:167], v[206:209], v[82:85]
	v_mfma_f32_16x16x32_bf16 v[74:77], v[156:159], v[214:217], v[74:77]
	v_mfma_f32_16x16x32_bf16 v[66:69], v[164:167], v[214:217], v[66:69]
	v_mfma_f32_16x16x32_bf16 v[122:125], v[160:163], v[192:195], v[122:125]
	v_mfma_f32_16x16x32_bf16 v[114:117], v[168:171], v[192:195], v[114:117]
	v_mfma_f32_16x16x32_bf16 v[106:109], v[160:163], v[202:205], v[106:109]
	v_mfma_f32_16x16x32_bf16 v[98:101], v[168:171], v[202:205], v[98:101]
	v_mfma_f32_16x16x32_bf16 v[90:93], v[160:163], v[210:213], v[90:93]
	v_mfma_f32_16x16x32_bf16 v[82:85], v[168:171], v[210:213], v[82:85]
	v_mfma_f32_16x16x32_bf16 v[74:77], v[160:163], v[218:221], v[74:77]
	v_mfma_f32_16x16x32_bf16 v[66:69], v[168:171], v[218:221], v[66:69]
	s_setprio 0
	s_setprio 1
	v_mfma_f32_16x16x32_bf16 v[126:129], v[172:175], v[188:191], v[126:129]
	v_mfma_f32_16x16x32_bf16 v[118:121], v[180:183], v[188:191], v[118:121]
	v_mfma_f32_16x16x32_bf16 v[110:113], v[172:175], v[198:201], v[110:113]
	v_mfma_f32_16x16x32_bf16 v[102:105], v[180:183], v[198:201], v[102:105]
	v_mfma_f32_16x16x32_bf16 v[94:97], v[172:175], v[206:209], v[94:97]
	v_mfma_f32_16x16x32_bf16 v[86:89], v[180:183], v[206:209], v[86:89]
	v_mfma_f32_16x16x32_bf16 v[78:81], v[172:175], v[214:217], v[78:81]
	v_mfma_f32_16x16x32_bf16 v[70:73], v[180:183], v[214:217], v[70:73]
	v_mfma_f32_16x16x32_bf16 v[126:129], v[176:179], v[192:195], v[126:129]
	v_mfma_f32_16x16x32_bf16 v[118:121], v[184:187], v[192:195], v[118:121]
	v_mfma_f32_16x16x32_bf16 v[110:113], v[176:179], v[202:205], v[110:113]
	v_mfma_f32_16x16x32_bf16 v[102:105], v[184:187], v[202:205], v[102:105]
	v_mfma_f32_16x16x32_bf16 v[94:97], v[176:179], v[210:213], v[94:97]
	v_mfma_f32_16x16x32_bf16 v[86:89], v[184:187], v[210:213], v[86:89]
	v_mfma_f32_16x16x32_bf16 v[78:81], v[176:179], v[218:221], v[78:81]
	v_mfma_f32_16x16x32_bf16 v[70:73], v[184:187], v[218:221], v[70:73]
	s_setprio 0
	s_barrier
	s_add_i32 s75, s63, s52
	v_lshl_add_u64 v[146:147], s[46:47], 0, v[134:135]
	s_mov_b32 m0, s75
	ds_read_b128 v[188:191], v154 offset:16384
	ds_read_b128 v[192:195], v154 offset:17408
	ds_read_b128 v[198:201], v154 offset:18432
	ds_read_b128 v[202:205], v154 offset:19456
	ds_read_b128 v[206:209], v154 offset:20480
	ds_read_b128 v[210:213], v154 offset:21504
	ds_read_b128 v[214:217], v154 offset:22528
	ds_read_b128 v[218:221], v154 offset:23552
	global_load_lds_dwordx4 v[146:147], off
	s_add_i32 m0, s75, 0x2000
	s_add_u32 s76, s46, 0x100000
	v_lshl_add_u64 v[222:223], s[46:47], 0, v[130:131]
	s_addc_u32 s77, s47, 0
	s_add_i32 s75, s67, s52
	global_load_lds_dwordx4 v[222:223], off
	v_lshl_add_u64 v[224:225], s[76:77], 0, v[134:135]
	s_mov_b32 m0, s75
	v_lshl_add_u64 v[226:227], s[48:49], 0, v[132:133]
	global_load_lds_dwordx4 v[224:225], off
	v_lshl_add_u64 v[224:225], s[76:77], 0, v[130:131]
	s_add_i32 m0, s75, 0x2000
	s_nop 0
	global_load_lds_dwordx4 v[224:225], off
	v_lshl_add_u64 v[224:225], s[48:49], 0, v[136:137]
	s_mov_b32 m0, s43
	s_nop 0
	global_load_lds_dwordx4 v[224:225], off
	s_mov_b32 m0, s55
	s_nop 0
	global_load_lds_dwordx4 v[226:227], off
	s_waitcnt vmcnt(8)
	s_waitcnt lgkmcnt(0)
	s_setprio 1
	s_barrier
; #define PG8_STAGE(bufoff, gbase, voff) do { _Pragma("unroll") for (int _i = 0; _i < 2; ++_i) \
;         __builtin_amdgcn_global_load_lds((const unsigned*)((const char*)(gbase) + (voff)[_i]), (PG8_LAS unsigned*)(lds + (bufoff) + ldsw + _i * 8192), 16, 0, 0); } while (0)
; #define PG8_LDA(dst, b, h) do { _Pragma("unroll") for (int m = 0; m < 4; ++m) _Pragma("unroll") for (int k = 0; k < 2; ++k) dst[m][k] = *(const PG8_LAS bf16x8*)(lds + PG8_SA(b, h) + aoff + m * 2048 + k * 1024); } while (0)
; #define PG8_LDB(dst, b, h) do { _Pragma("unroll") for (int n = 0; n < 2; ++n) _Pragma("unroll") for (int k = 0; k < 2; ++k) dst[n][k] = *(const PG8_LAS bf16x8*)(lds + PG8_SB(b, h) + boff + n * 2048 + k * 1024); } while (0)
; #define PG8_MMA(ai, bj, At, Bt) do { __builtin_amdgcn_s_setprio(1); _Pragma("unroll") for (int m = 0; m < 4; ++m) _Pragma("unroll") for (int n = 0; n < 2; ++n) _Pragma("unroll") for (int k = 0; k < 2; ++k) \
;         acc[ai][bj][m][n] = __builtin_amdgcn_mfma_f32_16x16x32_bf16(Bt[n][k], At[m][k], acc[ai][bj][m][n], 0, 0, 0); __builtin_amdgcn_s_setprio(0); } while (0)
; #define PG8_WAIT_V(n) asm volatile("s_waitcnt vmcnt(" #n ")" ::: "memory")
; #define PG8_WAIT_L(n) asm volatile("s_waitcnt lgkmcnt(" #n ")" ::: "memory")
; #define PG8_BAR __builtin_amdgcn_s_barrier()
; #define PG8_SCHED __builtin_amdgcn_sched_barrier(0)
; template <class Epi, class Sched, bool ALIGN_EPI = false, bool SP2 = false>
; __device__ __forceinline__ void gemm_phase(PG8_LAS unsigned char* lds, const Gemm g, const Sched& S, const Epi& E) {
;     ...
;             PG8_WAIT_V(8); PG8_WAIT_L(0); PG8_BAR; PG8_MMA(1, 0, At, B0); PG8_MMA(1, 1, At, B1); PG8_BAR; PG8_SCHED;
;             PG8_LDB(B0, 1, 0); PG8_LDB(B1, 1, 1); PG8_SCHED; PG8_LDA(At, 1, 0); PG8_STAGE(PG8_SA(0, 1), a2 + hstep, voffA);
;             PG8_WAIT_V(8); PG8_WAIT_L(0); PG8_BAR; PG8_MMA(0, 0, At, B0); PG8_MMA(0, 1, At, B1); PG8_BAR; PG8_SCHED;
	v_mfma_f32_16x16x32_bf16 v[58:61], v[156:159], v[188:191], v[58:61]
	v_mfma_f32_16x16x32_bf16 v[50:53], v[164:167], v[188:191], v[50:53]
	v_mfma_f32_16x16x32_bf16 v[42:45], v[156:159], v[198:201], v[42:45]
	v_mfma_f32_16x16x32_bf16 v[34:37], v[164:167], v[198:201], v[34:37]
	v_mfma_f32_16x16x32_bf16 v[26:29], v[156:159], v[206:209], v[26:29]
	v_mfma_f32_16x16x32_bf16 v[18:21], v[164:167], v[206:209], v[18:21]
	v_mfma_f32_16x16x32_bf16 v[10:13], v[156:159], v[214:217], v[10:13]
	v_mfma_f32_16x16x32_bf16 v[6:9], v[164:167], v[214:217], v[6:9]
	v_mfma_f32_16x16x32_bf16 v[58:61], v[160:163], v[192:195], v[58:61]
	v_mfma_f32_16x16x32_bf16 v[50:53], v[168:171], v[192:195], v[50:53]
	v_mfma_f32_16x16x32_bf16 v[42:45], v[160:163], v[202:205], v[42:45]
	v_mfma_f32_16x16x32_bf16 v[34:37], v[168:171], v[202:205], v[34:37]
	v_mfma_f32_16x16x32_bf16 v[26:29], v[160:163], v[210:213], v[26:29]
	v_mfma_f32_16x16x32_bf16 v[18:21], v[168:171], v[210:213], v[18:21]
	v_mfma_f32_16x16x32_bf16 v[10:13], v[160:163], v[218:221], v[10:13]
	v_mfma_f32_16x16x32_bf16 v[6:9], v[168:171], v[218:221], v[6:9]
	s_setprio 0
	s_setprio 1
	v_mfma_f32_16x16x32_bf16 v[62:65], v[172:175], v[188:191], v[62:65]
	v_mfma_f32_16x16x32_bf16 v[54:57], v[180:183], v[188:191], v[54:57]
	v_mfma_f32_16x16x32_bf16 v[46:49], v[172:175], v[198:201], v[46:49]
	v_mfma_f32_16x16x32_bf16 v[38:41], v[180:183], v[198:201], v[38:41]
	v_mfma_f32_16x16x32_bf16 v[30:33], v[172:175], v[206:209], v[30:33]
	v_mfma_f32_16x16x32_bf16 v[22:25], v[180:183], v[206:209], v[22:25]
	v_mfma_f32_16x16x32_bf16 v[14:17], v[172:175], v[214:217], v[14:17]
	v_mfma_f32_16x16x32_bf16 v[2:5], v[180:183], v[214:217], v[2:5]
	v_mfma_f32_16x16x32_bf16 v[62:65], v[176:179], v[192:195], v[62:65]
	v_mfma_f32_16x16x32_bf16 v[54:57], v[184:187], v[192:195], v[54:57]
	v_mfma_f32_16x16x32_bf16 v[46:49], v[176:179], v[202:205], v[46:49]
	v_mfma_f32_16x16x32_bf16 v[38:41], v[184:187], v[202:205], v[38:41]
	v_mfma_f32_16x16x32_bf16 v[30:33], v[176:179], v[210:213], v[30:33]
	v_mfma_f32_16x16x32_bf16 v[22:25], v[184:187], v[210:213], v[22:25]
	v_mfma_f32_16x16x32_bf16 v[14:17], v[176:179], v[218:221], v[14:17]
	v_mfma_f32_16x16x32_bf16 v[2:5], v[184:187], v[218:221], v[2:5]
	s_setprio 0
	s_barrier
	s_add_i32 s75, 0, 0x18000
	v_add_u32_e32 v155, s75, v150
	s_add_i32 s76, 0, 0x1c000
	ds_read_b128 v[156:159], v155
	ds_read_b128 v[160:163], v155 offset:1024
	ds_read_b128 v[164:167], v155 offset:2048
	ds_read_b128 v[168:171], v155 offset:3072
	v_add_u32_e32 v155, s76, v150
	ds_read_b128 v[172:175], v155
	ds_read_b128 v[176:179], v155 offset:1024
	ds_read_b128 v[180:183], v155 offset:2048
	ds_read_b128 v[184:187], v155 offset:3072
	s_add_u32 s48, s48, 0x100000
	s_addc_u32 s49, s49, 0
	s_mov_b32 m0, s56
	v_lshl_add_u64 v[228:229], s[48:49], 0, v[136:137]
	ds_read_b128 v[188:191], v154 offset:32768
	ds_read_b128 v[192:195], v154 offset:33792
	ds_read_b128 v[198:201], v154 offset:34816
	ds_read_b128 v[202:205], v154 offset:35840
	ds_read_b128 v[206:209], v154 offset:36864
	ds_read_b128 v[210:213], v154 offset:37888
	ds_read_b128 v[214:217], v154 offset:38912
	ds_read_b128 v[218:221], v154 offset:39936
	global_load_lds_dwordx4 v[228:229], off
	v_lshl_add_u64 v[228:229], s[48:49], 0, v[132:133]
	s_mov_b32 m0, s57
	s_nop 0
	global_load_lds_dwordx4 v[228:229], off
	s_waitcnt vmcnt(8)
	s_waitcnt lgkmcnt(0)
	s_setprio 1
	s_barrier
	v_mfma_f32_16x16x32_bf16 v[122:125], v[156:159], v[188:191], v[122:125]
	v_mfma_f32_16x16x32_bf16 v[114:117], v[164:167], v[188:191], v[114:117]
	v_mfma_f32_16x16x32_bf16 v[106:109], v[156:159], v[198:201], v[106:109]
	v_mfma_f32_16x16x32_bf16 v[98:101], v[164:167], v[198:201], v[98:101]
	v_mfma_f32_16x16x32_bf16 v[90:93], v[156:159], v[206:209], v[90:93]
	v_mfma_f32_16x16x32_bf16 v[82:85], v[164:167], v[206:209], v[82:85]
	v_mfma_f32_16x16x32_bf16 v[74:77], v[156:159], v[214:217], v[74:77]
	v_mfma_f32_16x16x32_bf16 v[66:69], v[164:167], v[214:217], v[66:69]
	v_mfma_f32_16x16x32_bf16 v[122:125], v[160:163], v[192:195], v[122:125]
	v_mfma_f32_16x16x32_bf16 v[114:117], v[168:171], v[192:195], v[114:117]
	v_mfma_f32_16x16x32_bf16 v[106:109], v[160:163], v[202:205], v[106:109]
	v_mfma_f32_16x16x32_bf16 v[98:101], v[168:171], v[202:205], v[98:101]
	v_mfma_f32_16x16x32_bf16 v[90:93], v[160:163], v[210:213], v[90:93]
	v_mfma_f32_16x16x32_bf16 v[82:85], v[168:171], v[210:213], v[82:85]
	v_mfma_f32_16x16x32_bf16 v[74:77], v[160:163], v[218:221], v[74:77]
	v_mfma_f32_16x16x32_bf16 v[66:69], v[168:171], v[218:221], v[66:69]
	s_setprio 0
	s_setprio 1
	v_mfma_f32_16x16x32_bf16 v[126:129], v[172:175], v[188:191], v[126:129]
	v_mfma_f32_16x16x32_bf16 v[118:121], v[180:183], v[188:191], v[118:121]
	v_mfma_f32_16x16x32_bf16 v[110:113], v[172:175], v[198:201], v[110:113]
	v_mfma_f32_16x16x32_bf16 v[102:105], v[180:183], v[198:201], v[102:105]
	v_mfma_f32_16x16x32_bf16 v[94:97], v[172:175], v[206:209], v[94:97]
	v_mfma_f32_16x16x32_bf16 v[86:89], v[180:183], v[206:209], v[86:89]
	v_mfma_f32_16x16x32_bf16 v[78:81], v[172:175], v[214:217], v[78:81]
	v_mfma_f32_16x16x32_bf16 v[70:73], v[180:183], v[214:217], v[70:73]
	v_mfma_f32_16x16x32_bf16 v[126:129], v[176:179], v[192:195], v[126:129]
	v_mfma_f32_16x16x32_bf16 v[118:121], v[184:187], v[192:195], v[118:121]
	v_mfma_f32_16x16x32_bf16 v[110:113], v[176:179], v[202:205], v[110:113]
	v_mfma_f32_16x16x32_bf16 v[102:105], v[184:187], v[202:205], v[102:105]
	v_mfma_f32_16x16x32_bf16 v[94:97], v[176:179], v[210:213], v[94:97]
	v_mfma_f32_16x16x32_bf16 v[86:89], v[184:187], v[210:213], v[86:89]
	v_mfma_f32_16x16x32_bf16 v[78:81], v[176:179], v[218:221], v[78:81]
	v_mfma_f32_16x16x32_bf16 v[70:73], v[184:187], v[218:221], v[70:73]
	s_setprio 0
	s_barrier
; #define PG8_STAGE(bufoff, gbase, voff) do { _Pragma("unroll") for (int _i = 0; _i < 2; ++_i) \
;         __builtin_amdgcn_global_load_lds((const unsigned*)((const char*)(gbase) + (voff)[_i]), (PG8_LAS unsigned*)(lds + (bufoff) + ldsw + _i * 8192), 16, 0, 0); } while (0)
; #define PG8_LDA(dst, b, h) do { _Pragma("unroll") for (int m = 0; m < 4; ++m) _Pragma("unroll") for (int k = 0; k < 2; ++k) dst[m][k] = *(const PG8_LAS bf16x8*)(lds + PG8_SA(b, h) + aoff + m * 2048 + k * 1024); } while (0)
; #define PG8_MMA(ai, bj, At, Bt) do { __builtin_amdgcn_s_setprio(1); _Pragma("unroll") for (int m = 0; m < 4; ++m) _Pragma("unroll") for (int n = 0; n < 2; ++n) _Pragma("unroll") for (int k = 0; k < 2; ++k) \
;         acc[ai][bj][m][n] = __builtin_amdgcn_mfma_f32_16x16x32_bf16(Bt[n][k], At[m][k], acc[ai][bj][m][n], 0, 0, 0); __builtin_amdgcn_s_setprio(0); } while (0)
; #define PG8_WAIT_V(n) asm volatile("s_waitcnt vmcnt(" #n ")" ::: "memory")
; #define PG8_WAIT_L(n) asm volatile("s_waitcnt lgkmcnt(" #n ")" ::: "memory")
; #define PG8_BAR __builtin_amdgcn_s_barrier()
; #define PG8_SCHED __builtin_amdgcn_sched_barrier(0)
; template <class Epi, class Sched, bool ALIGN_EPI = false, bool SP2 = false>
; __device__ __forceinline__ void gemm_phase(PG8_LAS unsigned char* lds, const Gemm g, const Sched& S, const Epi& E) {
;     ...
;             PG8_LDA(At, 1, 1); PG8_STAGE(PG8_SB(1, 0), b3, voffB); PG8_STAGE(PG8_SB(1, 1), b3 + hstep, voffB); PG8_STAGE(PG8_SA(1, 0), a3, voffA);
;             PG8_WAIT_V(8); PG8_WAIT_L(0); PG8_BAR; PG8_MMA(1, 0, At, B0); PG8_MMA(1, 1, At, B1); PG8_BAR; PG8_SCHED;
;     ...
;         if constexpr (ALIGN_EPI) { if (wr == 0) PG8_BAR; }
	s_add_i32 s48, s75, s52
	v_lshl_add_u64 v[146:147], v[146:147], 0, s[12:13]
	s_mov_b32 m0, s48
	ds_read_b128 v[188:191], v154 offset:49152
	ds_read_b128 v[192:195], v154 offset:50176
	ds_read_b128 v[198:201], v154 offset:51200
	ds_read_b128 v[202:205], v154 offset:52224
	ds_read_b128 v[206:209], v154 offset:53248
	ds_read_b128 v[210:213], v154 offset:54272
	ds_read_b128 v[214:217], v154 offset:55296
	ds_read_b128 v[218:221], v154 offset:56320
	global_load_lds_dwordx4 v[146:147], off
	s_add_i32 m0, s48, 0x2000
	s_add_u32 s46, s46, 0x100080
	v_lshl_add_u64 v[146:147], v[222:223], 0, s[12:13]
	s_addc_u32 s47, s47, 0
	s_add_i32 s48, s76, s52
	global_load_lds_dwordx4 v[146:147], off
	v_lshl_add_u64 v[146:147], s[46:47], 0, v[134:135]
	s_mov_b32 m0, s48
	s_nop 0
	global_load_lds_dwordx4 v[146:147], off
	v_lshl_add_u64 v[146:147], s[46:47], 0, v[130:131]
	s_add_i32 m0, s48, 0x2000
	s_nop 0
	global_load_lds_dwordx4 v[146:147], off
	v_lshl_add_u64 v[146:147], v[224:225], 0, s[12:13]
	s_mov_b32 m0, s59
	s_nop 0
	global_load_lds_dwordx4 v[146:147], off
	v_lshl_add_u64 v[146:147], v[226:227], 0, s[12:13]
	s_mov_b32 m0, s60
	s_nop 0
	global_load_lds_dwordx4 v[146:147], off
	s_waitcnt vmcnt(8)
	s_waitcnt lgkmcnt(0)
	s_setprio 1
	s_barrier
	v_mfma_f32_16x16x32_bf16 v[58:61], v[156:159], v[188:191], v[58:61]
	v_mfma_f32_16x16x32_bf16 v[50:53], v[164:167], v[188:191], v[50:53]
	v_mfma_f32_16x16x32_bf16 v[42:45], v[156:159], v[198:201], v[42:45]
	v_mfma_f32_16x16x32_bf16 v[34:37], v[164:167], v[198:201], v[34:37]
	v_mfma_f32_16x16x32_bf16 v[26:29], v[156:159], v[206:209], v[26:29]
	v_mfma_f32_16x16x32_bf16 v[18:21], v[164:167], v[206:209], v[18:21]
	v_mfma_f32_16x16x32_bf16 v[10:13], v[156:159], v[214:217], v[10:13]
	v_mfma_f32_16x16x32_bf16 v[6:9], v[164:167], v[214:217], v[6:9]
	v_mfma_f32_16x16x32_bf16 v[58:61], v[160:163], v[192:195], v[58:61]
	v_mfma_f32_16x16x32_bf16 v[50:53], v[168:171], v[192:195], v[50:53]
	v_mfma_f32_16x16x32_bf16 v[42:45], v[160:163], v[202:205], v[42:45]
	v_mfma_f32_16x16x32_bf16 v[34:37], v[168:171], v[202:205], v[34:37]
	v_mfma_f32_16x16x32_bf16 v[26:29], v[160:163], v[210:213], v[26:29]
	v_mfma_f32_16x16x32_bf16 v[18:21], v[168:171], v[210:213], v[18:21]
	v_mfma_f32_16x16x32_bf16 v[10:13], v[160:163], v[218:221], v[10:13]
	v_mfma_f32_16x16x32_bf16 v[6:9], v[168:171], v[218:221], v[6:9]
	s_setprio 0
	s_setprio 1
	v_mfma_f32_16x16x32_bf16 v[62:65], v[172:175], v[188:191], v[62:65]
	v_mfma_f32_16x16x32_bf16 v[54:57], v[180:183], v[188:191], v[54:57]
	v_mfma_f32_16x16x32_bf16 v[46:49], v[172:175], v[198:201], v[46:49]
	v_mfma_f32_16x16x32_bf16 v[38:41], v[180:183], v[198:201], v[38:41]
	v_mfma_f32_16x16x32_bf16 v[30:33], v[172:175], v[206:209], v[30:33]
	v_mfma_f32_16x16x32_bf16 v[22:25], v[180:183], v[206:209], v[22:25]
	v_mfma_f32_16x16x32_bf16 v[14:17], v[172:175], v[214:217], v[14:17]
	v_mfma_f32_16x16x32_bf16 v[2:5], v[180:183], v[214:217], v[2:5]
	v_mfma_f32_16x16x32_bf16 v[62:65], v[176:179], v[192:195], v[62:65]
	v_mfma_f32_16x16x32_bf16 v[54:57], v[184:187], v[192:195], v[54:57]
	v_mfma_f32_16x16x32_bf16 v[46:49], v[176:179], v[202:205], v[46:49]
	v_mfma_f32_16x16x32_bf16 v[38:41], v[184:187], v[202:205], v[38:41]
	v_mfma_f32_16x16x32_bf16 v[30:33], v[176:179], v[210:213], v[30:33]
	v_mfma_f32_16x16x32_bf16 v[22:25], v[184:187], v[210:213], v[22:25]
	v_mfma_f32_16x16x32_bf16 v[14:17], v[176:179], v[218:221], v[14:17]
	v_mfma_f32_16x16x32_bf16 v[2:5], v[184:187], v[218:221], v[2:5]
	s_setprio 0
	s_barrier
	s_add_i32 s74, s74, 2
	s_add_u32 s44, s44, 0x100
	s_addc_u32 s45, s45, 0
	s_add_u32 s72, s72, 0x100
	s_addc_u32 s73, s73, 0
	s_cmp_gt_u32 s74, 61
	s_cbranch_scc0 .LBB0_881
	s_and_b64 vcc, exec, s[16:17]
	s_cbranch_vccz .LBB0_884
	s_barrier

; #define PG8_STAGE(bufoff, gbase, voff) do { _Pragma("unroll") for (int _i = 0; _i < 2; ++_i) \
;         __builtin_amdgcn_global_load_lds((const unsigned*)((const char*)(gbase) + (voff)[_i]), (PG8_LAS unsigned*)(lds + (bufoff) + ldsw + _i * 8192), 16, 0, 0); } while (0)
; #define PG8_LDA(dst, b, h) do { _Pragma("unroll") for (int m = 0; m < 4; ++m) _Pragma("unroll") for (int k = 0; k < 2; ++k) dst[m][k] = *(const PG8_LAS bf16x8*)(lds + PG8_SA(b, h) + aoff + m * 2048 + k * 1024); } while (0)
; #define PG8_LDB(dst, b, h) do { _Pragma("unroll") for (int n = 0; n < 2; ++n) _Pragma("unroll") for (int k = 0; k < 2; ++k) dst[n][k] = *(const PG8_LAS bf16x8*)(lds + PG8_SB(b, h) + boff + n * 2048 + k * 1024); } while (0)
; #define PG8_MMA(ai, bj, At, Bt) do { __builtin_amdgcn_s_setprio(1); _Pragma("unroll") for (int m = 0; m < 4; ++m) _Pragma("unroll") for (int n = 0; n < 2; ++n) _Pragma("unroll") for (int k = 0; k < 2; ++k) \
;         acc[ai][bj][m][n] = __builtin_amdgcn_mfma_f32_16x16x32_bf16(Bt[n][k], At[m][k], acc[ai][bj][m][n], 0, 0, 0); __builtin_amdgcn_s_setprio(0); } while (0)
; #define PG8_WAIT_V(n) asm volatile("s_waitcnt vmcnt(" #n ")" ::: "memory")
; #define PG8_WAIT_L(n) asm volatile("s_waitcnt lgkmcnt(" #n ")" ::: "memory")
; template <class Epi, class Sched, bool ALIGN_EPI = false, bool SP2 = false>
; __device__ __forceinline__ void gemm_phase(PG8_LAS unsigned char* lds, const Gemm g, const Sched& S, const Epi& E) {
;     ...
;             const bool last = (t == nt - 2);
;             const char* a1 = cA + (size_t)(t + 1) * kstep;
;             const char* a2 = last ? nA : cA + (size_t)(t + 2) * kstep; const char* b2 = last ? nB : cB + (size_t)(t + 2) * kstep;
;             const char* a3 = a2 + kstep; const char* b3 = b2 + kstep;
;             if (last && has_next) S.a_ready(nxt);
;             if constexpr (SP2) {
;             PG8_LDB(B0, 0, 0); PG8_LDB(B1, 0, 1); PG8_SCHED; PG8_LDA(At, 0, 0); PG8_STAGE(PG8_SA(1, 1), a1 + hstep, voffA);
;             PG8_WAIT_V(8); PG8_WAIT_L(0); PG8_BAR; PG8_MMA(0, 0, At, B0); PG8_MMA(0, 1, At, B1); PG8_BAR; PG8_SCHED;
;             PG8_LDA(At, 0, 1); PG8_STAGE(PG8_SB(0, 0), b2, voffB); PG8_STAGE(PG8_SB(0, 1), b2 + hstep, voffB); PG8_STAGE(PG8_SA(0, 0), a2, voffA);
;             PG8_WAIT_V(8); PG8_WAIT_L(0); PG8_BAR; PG8_MMA(1, 0, At, B0); PG8_MMA(1, 1, At, B1); PG8_BAR; PG8_SCHED;
.LBB0_984:
	ds_read_b128 v[146:149], v160
	ds_read_b128 v[164:167], v160 offset:1024
	ds_read_b128 v[168:171], v160 offset:2048
	ds_read_b128 v[172:175], v160 offset:3072
	ds_read_b128 v[176:179], v161
	ds_read_b128 v[180:183], v161 offset:1024
	ds_read_b128 v[184:187], v161 offset:2048
	ds_read_b128 v[188:191], v161 offset:3072
	s_add_u32 s44, s42, 0xffd50080
	s_addc_u32 s45, s43, -1
	s_cmpk_eq_i32 s71, 0xa8
	s_cselect_b32 s47, s7, s45
	s_cselect_b32 s46, s6, s44
	s_cselect_b32 s45, s41, s70
	s_cselect_b32 s44, s40, s69
	v_lshl_add_u64 v[226:227], s[42:43], 0, v[138:139]
	s_add_i32 m0, s52, 0xc000
	ds_read_b128 v[192:195], v162
	ds_read_b128 v[198:201], v162 offset:1024
	ds_read_b128 v[202:205], v162 offset:2048
	ds_read_b128 v[206:209], v162 offset:3072
	ds_read_b128 v[210:213], v162 offset:4096
	ds_read_b128 v[214:217], v162 offset:5120
	ds_read_b128 v[218:221], v162 offset:6144
	ds_read_b128 v[222:225], v162 offset:7168
	global_load_lds_dwordx4 v[226:227], off
	v_lshl_add_u64 v[226:227], s[42:43], 0, v[140:141]
	s_add_i32 m0, s52, 0xe000
	s_nop 0
	global_load_lds_dwordx4 v[226:227], off
	s_waitcnt vmcnt(8)
	s_waitcnt lgkmcnt(0)
	s_setprio 1
	s_barrier
	v_mfma_f32_16x16x32_bf16 v[126:129], v[146:149], v[192:195], v[126:129]
	v_mfma_f32_16x16x32_bf16 v[122:125], v[168:171], v[192:195], v[122:125]
	v_mfma_f32_16x16x32_bf16 v[110:113], v[146:149], v[202:205], v[110:113]
	v_mfma_f32_16x16x32_bf16 v[106:109], v[168:171], v[202:205], v[106:109]
	v_mfma_f32_16x16x32_bf16 v[94:97], v[146:149], v[210:213], v[94:97]
	v_mfma_f32_16x16x32_bf16 v[90:93], v[168:171], v[210:213], v[90:93]
	v_mfma_f32_16x16x32_bf16 v[78:81], v[146:149], v[218:221], v[78:81]
	v_mfma_f32_16x16x32_bf16 v[74:77], v[168:171], v[218:221], v[74:77]
	v_mfma_f32_16x16x32_bf16 v[126:129], v[164:167], v[198:201], v[126:129]
	v_mfma_f32_16x16x32_bf16 v[122:125], v[172:175], v[198:201], v[122:125]
	v_mfma_f32_16x16x32_bf16 v[110:113], v[164:167], v[206:209], v[110:113]
	v_mfma_f32_16x16x32_bf16 v[106:109], v[172:175], v[206:209], v[106:109]
	v_mfma_f32_16x16x32_bf16 v[94:97], v[164:167], v[214:217], v[94:97]
	v_mfma_f32_16x16x32_bf16 v[90:93], v[172:175], v[214:217], v[90:93]
	v_mfma_f32_16x16x32_bf16 v[78:81], v[164:167], v[222:225], v[78:81]
	v_mfma_f32_16x16x32_bf16 v[74:77], v[172:175], v[222:225], v[74:77]
	s_setprio 0
	s_setprio 1
	v_mfma_f32_16x16x32_bf16 v[118:121], v[176:179], v[192:195], v[118:121]
	v_mfma_f32_16x16x32_bf16 v[114:117], v[184:187], v[192:195], v[114:117]
	v_mfma_f32_16x16x32_bf16 v[102:105], v[176:179], v[202:205], v[102:105]
	v_mfma_f32_16x16x32_bf16 v[98:101], v[184:187], v[202:205], v[98:101]
	v_mfma_f32_16x16x32_bf16 v[86:89], v[176:179], v[210:213], v[86:89]
	v_mfma_f32_16x16x32_bf16 v[82:85], v[184:187], v[210:213], v[82:85]
	v_mfma_f32_16x16x32_bf16 v[70:73], v[176:179], v[218:221], v[70:73]
	v_mfma_f32_16x16x32_bf16 v[66:69], v[184:187], v[218:221], v[66:69]
	v_mfma_f32_16x16x32_bf16 v[118:121], v[180:183], v[198:201], v[118:121]
	v_mfma_f32_16x16x32_bf16 v[114:117], v[188:191], v[198:201], v[114:117]
	v_mfma_f32_16x16x32_bf16 v[102:105], v[180:183], v[206:209], v[102:105]
	v_mfma_f32_16x16x32_bf16 v[98:101], v[188:191], v[206:209], v[98:101]
	v_mfma_f32_16x16x32_bf16 v[86:89], v[180:183], v[214:217], v[86:89]
	v_mfma_f32_16x16x32_bf16 v[82:85], v[188:191], v[214:217], v[82:85]
	v_mfma_f32_16x16x32_bf16 v[70:73], v[180:183], v[222:225], v[70:73]
	v_mfma_f32_16x16x32_bf16 v[66:69], v[188:191], v[222:225], v[66:69]
	s_setprio 0
	s_barrier
	s_add_i32 s72, s62, s51
	v_lshl_add_u64 v[226:227], s[44:45], 0, v[132:133]
	s_mov_b32 m0, s72
	ds_read_b128 v[192:195], v162 offset:16384
	ds_read_b128 v[198:201], v162 offset:17408
	ds_read_b128 v[202:205], v162 offset:18432
	ds_read_b128 v[206:209], v162 offset:19456
	ds_read_b128 v[210:213], v162 offset:20480
	ds_read_b128 v[214:217], v162 offset:21504
	ds_read_b128 v[218:221], v162 offset:22528
	ds_read_b128 v[222:225], v162 offset:23552
	global_load_lds_dwordx4 v[226:227], off
	s_add_i32 m0, s72, 0x2000
	s_add_u32 s72, s44, 0x2b0000
	v_lshl_add_u64 v[228:229], s[44:45], 0, v[136:137]
	s_addc_u32 s73, s45, 0
	s_add_i32 s74, s63, s51
	global_load_lds_dwordx4 v[228:229], off
	v_lshl_add_u64 v[230:231], s[72:73], 0, v[132:133]
	s_mov_b32 m0, s74
	v_lshl_add_u64 v[232:233], s[46:47], 0, v[134:135]
	global_load_lds_dwordx4 v[230:231], off
	v_lshl_add_u64 v[230:231], s[72:73], 0, v[136:137]
	s_add_i32 m0, s74, 0x2000
	s_nop 0
	global_load_lds_dwordx4 v[230:231], off
	v_lshl_add_u64 v[230:231], s[46:47], 0, v[130:131]
	s_mov_b32 m0, s52
	s_nop 0
	global_load_lds_dwordx4 v[230:231], off
	s_mov_b32 m0, s53
	s_nop 0
	global_load_lds_dwordx4 v[232:233], off
	s_waitcnt vmcnt(8)
	s_waitcnt lgkmcnt(0)
	s_setprio 1
	s_barrier
; #define PG8_STAGE(bufoff, gbase, voff) do { _Pragma("unroll") for (int _i = 0; _i < 2; ++_i) \
;         __builtin_amdgcn_global_load_lds((const unsigned*)((const char*)(gbase) + (voff)[_i]), (PG8_LAS unsigned*)(lds + (bufoff) + ldsw + _i * 8192), 16, 0, 0); } while (0)
; #define PG8_LDA(dst, b, h) do { _Pragma("unroll") for (int m = 0; m < 4; ++m) _Pragma("unroll") for (int k = 0; k < 2; ++k) dst[m][k] = *(const PG8_LAS bf16x8*)(lds + PG8_SA(b, h) + aoff + m * 2048 + k * 1024); } while (0)
; #define PG8_LDB(dst, b, h) do { _Pragma("unroll") for (int n = 0; n < 2; ++n) _Pragma("unroll") for (int k = 0; k < 2; ++k) dst[n][k] = *(const PG8_LAS bf16x8*)(lds + PG8_SB(b, h) + boff + n * 2048 + k * 1024); } while (0)
; #define PG8_MMA(ai, bj, At, Bt) do { __builtin_amdgcn_s_setprio(1); _Pragma("unroll") for (int m = 0; m < 4; ++m) _Pragma("unroll") for (int n = 0; n < 2; ++n) _Pragma("unroll") for (int k = 0; k < 2; ++k) \
;         acc[ai][bj][m][n] = __builtin_amdgcn_mfma_f32_16x16x32_bf16(Bt[n][k], At[m][k], acc[ai][bj][m][n], 0, 0, 0); __builtin_amdgcn_s_setprio(0); } while (0)
; #define PG8_WAIT_V(n) asm volatile("s_waitcnt vmcnt(" #n ")" ::: "memory")
; #define PG8_WAIT_L(n) asm volatile("s_waitcnt lgkmcnt(" #n ")" ::: "memory")
; #define PG8_BAR __builtin_amdgcn_s_barrier()
; #define PG8_SCHED __builtin_amdgcn_sched_barrier(0)
; template <class Epi, class Sched, bool ALIGN_EPI = false, bool SP2 = false>
; __device__ __forceinline__ void gemm_phase(PG8_LAS unsigned char* lds, const Gemm g, const Sched& S, const Epi& E) {
;     ...
;             PG8_WAIT_V(8); PG8_WAIT_L(0); PG8_BAR; PG8_MMA(1, 0, At, B0); PG8_MMA(1, 1, At, B1); PG8_BAR; PG8_SCHED;
;             PG8_LDB(B0, 1, 0); PG8_LDB(B1, 1, 1); PG8_SCHED; PG8_LDA(At, 1, 0); PG8_STAGE(PG8_SA(0, 1), a2 + hstep, voffA);
;             PG8_WAIT_V(8); PG8_WAIT_L(0); PG8_BAR; PG8_MMA(0, 0, At, B0); PG8_MMA(0, 1, At, B1); PG8_BAR; PG8_SCHED;
	v_mfma_f32_16x16x32_bf16 v[62:65], v[146:149], v[192:195], v[62:65]
	v_mfma_f32_16x16x32_bf16 v[58:61], v[168:171], v[192:195], v[58:61]
	v_mfma_f32_16x16x32_bf16 v[46:49], v[146:149], v[202:205], v[46:49]
	v_mfma_f32_16x16x32_bf16 v[42:45], v[168:171], v[202:205], v[42:45]
	v_mfma_f32_16x16x32_bf16 v[30:33], v[146:149], v[210:213], v[30:33]
	v_mfma_f32_16x16x32_bf16 v[26:29], v[168:171], v[210:213], v[26:29]
	v_mfma_f32_16x16x32_bf16 v[14:17], v[146:149], v[218:221], v[14:17]
	v_mfma_f32_16x16x32_bf16 v[10:13], v[168:171], v[218:221], v[10:13]
	v_mfma_f32_16x16x32_bf16 v[62:65], v[164:167], v[198:201], v[62:65]
	v_mfma_f32_16x16x32_bf16 v[58:61], v[172:175], v[198:201], v[58:61]
	v_mfma_f32_16x16x32_bf16 v[46:49], v[164:167], v[206:209], v[46:49]
	v_mfma_f32_16x16x32_bf16 v[42:45], v[172:175], v[206:209], v[42:45]
	v_mfma_f32_16x16x32_bf16 v[30:33], v[164:167], v[214:217], v[30:33]
	v_mfma_f32_16x16x32_bf16 v[26:29], v[172:175], v[214:217], v[26:29]
	v_mfma_f32_16x16x32_bf16 v[14:17], v[164:167], v[222:225], v[14:17]
	v_mfma_f32_16x16x32_bf16 v[10:13], v[172:175], v[222:225], v[10:13]
	s_setprio 0
	s_setprio 1
	v_mfma_f32_16x16x32_bf16 v[54:57], v[176:179], v[192:195], v[54:57]
	v_mfma_f32_16x16x32_bf16 v[50:53], v[184:187], v[192:195], v[50:53]
	v_mfma_f32_16x16x32_bf16 v[38:41], v[176:179], v[202:205], v[38:41]
	v_mfma_f32_16x16x32_bf16 v[34:37], v[184:187], v[202:205], v[34:37]
	v_mfma_f32_16x16x32_bf16 v[22:25], v[176:179], v[210:213], v[22:25]
	v_mfma_f32_16x16x32_bf16 v[18:21], v[184:187], v[210:213], v[18:21]
	v_mfma_f32_16x16x32_bf16 v[6:9], v[176:179], v[218:221], v[6:9]
	v_mfma_f32_16x16x32_bf16 v[2:5], v[184:187], v[218:221], v[2:5]
	v_mfma_f32_16x16x32_bf16 v[54:57], v[180:183], v[198:201], v[54:57]
	v_mfma_f32_16x16x32_bf16 v[50:53], v[188:191], v[198:201], v[50:53]
	v_mfma_f32_16x16x32_bf16 v[38:41], v[180:183], v[206:209], v[38:41]
	v_mfma_f32_16x16x32_bf16 v[34:37], v[188:191], v[206:209], v[34:37]
	v_mfma_f32_16x16x32_bf16 v[22:25], v[180:183], v[214:217], v[22:25]
	v_mfma_f32_16x16x32_bf16 v[18:21], v[188:191], v[214:217], v[18:21]
	v_mfma_f32_16x16x32_bf16 v[6:9], v[180:183], v[222:225], v[6:9]
	v_mfma_f32_16x16x32_bf16 v[2:5], v[188:191], v[222:225], v[2:5]
	s_setprio 0
	s_barrier
	s_add_i32 s72, 0, 0x18000
	s_add_i32 s73, 0, 0x1c000
	v_add_u32_e32 v172, s72, v151
	v_add_u32_e32 v188, s73, v151
	ds_read_b128 v[146:149], v172
	ds_read_b128 v[164:167], v172 offset:1024
	ds_read_b128 v[168:171], v172 offset:2048
	ds_read_b128 v[172:175], v172 offset:3072
	ds_read_b128 v[176:179], v188
	ds_read_b128 v[180:183], v188 offset:1024
	ds_read_b128 v[184:187], v188 offset:2048
	ds_read_b128 v[188:191], v188 offset:3072
	s_add_u32 s46, s46, 0x2b0000
	s_addc_u32 s47, s47, 0
	s_mov_b32 m0, s54
	v_lshl_add_u64 v[234:235], s[46:47], 0, v[130:131]
	ds_read_b128 v[192:195], v162 offset:32768
	ds_read_b128 v[198:201], v162 offset:33792
	ds_read_b128 v[202:205], v162 offset:34816
	ds_read_b128 v[206:209], v162 offset:35840
	ds_read_b128 v[210:213], v162 offset:36864
	ds_read_b128 v[214:217], v162 offset:37888
	ds_read_b128 v[218:221], v162 offset:38912
	ds_read_b128 v[222:225], v162 offset:39936
	global_load_lds_dwordx4 v[234:235], off
	v_lshl_add_u64 v[234:235], s[46:47], 0, v[134:135]
	s_mov_b32 m0, s55
	s_nop 0
	global_load_lds_dwordx4 v[234:235], off
	s_waitcnt vmcnt(8)
	s_waitcnt lgkmcnt(0)
	s_setprio 1
	s_barrier
	v_mfma_f32_16x16x32_bf16 v[126:129], v[146:149], v[192:195], v[126:129]
	v_mfma_f32_16x16x32_bf16 v[122:125], v[168:171], v[192:195], v[122:125]
	v_mfma_f32_16x16x32_bf16 v[110:113], v[146:149], v[202:205], v[110:113]
	v_mfma_f32_16x16x32_bf16 v[106:109], v[168:171], v[202:205], v[106:109]
	v_mfma_f32_16x16x32_bf16 v[94:97], v[146:149], v[210:213], v[94:97]
	v_mfma_f32_16x16x32_bf16 v[90:93], v[168:171], v[210:213], v[90:93]
	v_mfma_f32_16x16x32_bf16 v[78:81], v[146:149], v[218:221], v[78:81]
	v_mfma_f32_16x16x32_bf16 v[74:77], v[168:171], v[218:221], v[74:77]
	v_mfma_f32_16x16x32_bf16 v[126:129], v[164:167], v[198:201], v[126:129]
	v_mfma_f32_16x16x32_bf16 v[122:125], v[172:175], v[198:201], v[122:125]
	v_mfma_f32_16x16x32_bf16 v[110:113], v[164:167], v[206:209], v[110:113]
	v_mfma_f32_16x16x32_bf16 v[106:109], v[172:175], v[206:209], v[106:109]
	v_mfma_f32_16x16x32_bf16 v[94:97], v[164:167], v[214:217], v[94:97]
	v_mfma_f32_16x16x32_bf16 v[90:93], v[172:175], v[214:217], v[90:93]
	v_mfma_f32_16x16x32_bf16 v[78:81], v[164:167], v[222:225], v[78:81]
	v_mfma_f32_16x16x32_bf16 v[74:77], v[172:175], v[222:225], v[74:77]
	s_setprio 0
	s_setprio 1
	v_mfma_f32_16x16x32_bf16 v[118:121], v[176:179], v[192:195], v[118:121]
	v_mfma_f32_16x16x32_bf16 v[114:117], v[184:187], v[192:195], v[114:117]
	v_mfma_f32_16x16x32_bf16 v[102:105], v[176:179], v[202:205], v[102:105]
	v_mfma_f32_16x16x32_bf16 v[98:101], v[184:187], v[202:205], v[98:101]
	v_mfma_f32_16x16x32_bf16 v[86:89], v[176:179], v[210:213], v[86:89]
	v_mfma_f32_16x16x32_bf16 v[82:85], v[184:187], v[210:213], v[82:85]
	v_mfma_f32_16x16x32_bf16 v[70:73], v[176:179], v[218:221], v[70:73]
	v_mfma_f32_16x16x32_bf16 v[66:69], v[184:187], v[218:221], v[66:69]
	v_mfma_f32_16x16x32_bf16 v[118:121], v[180:183], v[198:201], v[118:121]
	v_mfma_f32_16x16x32_bf16 v[114:117], v[188:191], v[198:201], v[114:117]
	v_mfma_f32_16x16x32_bf16 v[102:105], v[180:183], v[206:209], v[102:105]
	v_mfma_f32_16x16x32_bf16 v[98:101], v[188:191], v[206:209], v[98:101]
	v_mfma_f32_16x16x32_bf16 v[86:89], v[180:183], v[214:217], v[86:89]
	v_mfma_f32_16x16x32_bf16 v[82:85], v[188:191], v[214:217], v[82:85]
	v_mfma_f32_16x16x32_bf16 v[70:73], v[180:183], v[222:225], v[70:73]
	v_mfma_f32_16x16x32_bf16 v[66:69], v[188:191], v[222:225], v[66:69]
	s_setprio 0
	s_barrier
; #define PG8_STAGE(bufoff, gbase, voff) do { _Pragma("unroll") for (int _i = 0; _i < 2; ++_i) \
;         __builtin_amdgcn_global_load_lds((const unsigned*)((const char*)(gbase) + (voff)[_i]), (PG8_LAS unsigned*)(lds + (bufoff) + ldsw + _i * 8192), 16, 0, 0); } while (0)
; #define PG8_LDA(dst, b, h) do { _Pragma("unroll") for (int m = 0; m < 4; ++m) _Pragma("unroll") for (int k = 0; k < 2; ++k) dst[m][k] = *(const PG8_LAS bf16x8*)(lds + PG8_SA(b, h) + aoff + m * 2048 + k * 1024); } while (0)
; #define PG8_MMA(ai, bj, At, Bt) do { __builtin_amdgcn_s_setprio(1); _Pragma("unroll") for (int m = 0; m < 4; ++m) _Pragma("unroll") for (int n = 0; n < 2; ++n) _Pragma("unroll") for (int k = 0; k < 2; ++k) \
;         acc[ai][bj][m][n] = __builtin_amdgcn_mfma_f32_16x16x32_bf16(Bt[n][k], At[m][k], acc[ai][bj][m][n], 0, 0, 0); __builtin_amdgcn_s_setprio(0); } while (0)
; #define PG8_WAIT_V(n) asm volatile("s_waitcnt vmcnt(" #n ")" ::: "memory")
; #define PG8_WAIT_L(n) asm volatile("s_waitcnt lgkmcnt(" #n ")" ::: "memory")
; #define PG8_BAR __builtin_amdgcn_s_barrier()
; #define PG8_SCHED __builtin_amdgcn_sched_barrier(0)
; template <class Epi, class Sched, bool ALIGN_EPI = false, bool SP2 = false>
; __device__ __forceinline__ void gemm_phase(PG8_LAS unsigned char* lds, const Gemm g, const Sched& S, const Epi& E) {
;     ...
;             PG8_LDA(At, 1, 1); PG8_STAGE(PG8_SB(1, 0), b3, voffB); PG8_STAGE(PG8_SB(1, 1), b3 + hstep, voffB); PG8_STAGE(PG8_SA(1, 0), a3, voffA);
;             PG8_WAIT_V(8); PG8_WAIT_L(0); PG8_BAR; PG8_MMA(1, 0, At, B0); PG8_MMA(1, 1, At, B1); PG8_BAR; PG8_SCHED;
;     ...
;         if constexpr (ALIGN_EPI) { if (wr == 0) PG8_BAR; }
	s_add_i32 s46, s72, s51
	v_lshl_add_u64 v[226:227], v[226:227], 0, s[36:37]
	s_mov_b32 m0, s46
	ds_read_b128 v[192:195], v162 offset:49152
	ds_read_b128 v[198:201], v162 offset:50176
	ds_read_b128 v[202:205], v162 offset:51200
	ds_read_b128 v[206:209], v162 offset:52224
	ds_read_b128 v[210:213], v162 offset:53248
	ds_read_b128 v[214:217], v162 offset:54272
	ds_read_b128 v[218:221], v162 offset:55296
	ds_read_b128 v[222:225], v162 offset:56320
	global_load_lds_dwordx4 v[226:227], off
	s_add_i32 m0, s46, 0x2000
	s_add_u32 s44, s44, 0x2b0080
	v_lshl_add_u64 v[226:227], v[228:229], 0, s[36:37]
	s_addc_u32 s45, s45, 0
	s_add_i32 s46, s73, s51
	global_load_lds_dwordx4 v[226:227], off
	v_lshl_add_u64 v[226:227], s[44:45], 0, v[132:133]
	s_mov_b32 m0, s46
	s_nop 0
	global_load_lds_dwordx4 v[226:227], off
	v_lshl_add_u64 v[226:227], s[44:45], 0, v[136:137]
	s_add_i32 m0, s46, 0x2000
	s_nop 0
	global_load_lds_dwordx4 v[226:227], off
	v_lshl_add_u64 v[226:227], v[230:231], 0, s[36:37]
	s_mov_b32 m0, s57
	s_nop 0
	global_load_lds_dwordx4 v[226:227], off
	v_lshl_add_u64 v[226:227], v[232:233], 0, s[36:37]
	s_mov_b32 m0, s58
	s_nop 0
	global_load_lds_dwordx4 v[226:227], off
	s_waitcnt vmcnt(8)
	s_waitcnt lgkmcnt(0)
	s_setprio 1
	s_barrier
	v_mfma_f32_16x16x32_bf16 v[62:65], v[146:149], v[192:195], v[62:65]
	v_mfma_f32_16x16x32_bf16 v[58:61], v[168:171], v[192:195], v[58:61]
	v_mfma_f32_16x16x32_bf16 v[46:49], v[146:149], v[202:205], v[46:49]
	v_mfma_f32_16x16x32_bf16 v[42:45], v[168:171], v[202:205], v[42:45]
	v_mfma_f32_16x16x32_bf16 v[30:33], v[146:149], v[210:213], v[30:33]
	v_mfma_f32_16x16x32_bf16 v[26:29], v[168:171], v[210:213], v[26:29]
	v_mfma_f32_16x16x32_bf16 v[14:17], v[146:149], v[218:221], v[14:17]
	v_mfma_f32_16x16x32_bf16 v[10:13], v[168:171], v[218:221], v[10:13]
	v_mfma_f32_16x16x32_bf16 v[62:65], v[164:167], v[198:201], v[62:65]
	v_mfma_f32_16x16x32_bf16 v[58:61], v[172:175], v[198:201], v[58:61]
	v_mfma_f32_16x16x32_bf16 v[46:49], v[164:167], v[206:209], v[46:49]
	v_mfma_f32_16x16x32_bf16 v[42:45], v[172:175], v[206:209], v[42:45]
	v_mfma_f32_16x16x32_bf16 v[30:33], v[164:167], v[214:217], v[30:33]
	v_mfma_f32_16x16x32_bf16 v[26:29], v[172:175], v[214:217], v[26:29]
	v_mfma_f32_16x16x32_bf16 v[14:17], v[164:167], v[222:225], v[14:17]
	v_mfma_f32_16x16x32_bf16 v[10:13], v[172:175], v[222:225], v[10:13]
	s_setprio 0
	s_setprio 1
	v_mfma_f32_16x16x32_bf16 v[54:57], v[176:179], v[192:195], v[54:57]
	v_mfma_f32_16x16x32_bf16 v[50:53], v[184:187], v[192:195], v[50:53]
	v_mfma_f32_16x16x32_bf16 v[38:41], v[176:179], v[202:205], v[38:41]
	v_mfma_f32_16x16x32_bf16 v[34:37], v[184:187], v[202:205], v[34:37]
	v_mfma_f32_16x16x32_bf16 v[22:25], v[176:179], v[210:213], v[22:25]
	v_mfma_f32_16x16x32_bf16 v[18:21], v[184:187], v[210:213], v[18:21]
	v_mfma_f32_16x16x32_bf16 v[6:9], v[176:179], v[218:221], v[6:9]
	v_mfma_f32_16x16x32_bf16 v[2:5], v[184:187], v[218:221], v[2:5]
	v_mfma_f32_16x16x32_bf16 v[54:57], v[180:183], v[198:201], v[54:57]
	v_mfma_f32_16x16x32_bf16 v[50:53], v[188:191], v[198:201], v[50:53]
	v_mfma_f32_16x16x32_bf16 v[38:41], v[180:183], v[206:209], v[38:41]
	v_mfma_f32_16x16x32_bf16 v[34:37], v[188:191], v[206:209], v[34:37]
	v_mfma_f32_16x16x32_bf16 v[22:25], v[180:183], v[214:217], v[22:25]
	v_mfma_f32_16x16x32_bf16 v[18:21], v[188:191], v[214:217], v[18:21]
	v_mfma_f32_16x16x32_bf16 v[6:9], v[180:183], v[222:225], v[6:9]
	v_mfma_f32_16x16x32_bf16 v[2:5], v[188:191], v[222:225], v[2:5]
	s_setprio 0
	s_barrier
	s_add_i32 s71, s71, 2
	s_add_u32 s42, s42, 0x100
	s_addc_u32 s43, s43, 0
	s_add_u32 s69, s69, 0x100
	s_addc_u32 s70, s70, 0
	s_cmpk_gt_u32 s71, 0xa9
	s_cbranch_scc0 .LBB0_984
	s_and_b64 vcc, exec, s[38:39]
	s_cbranch_vccz .LBB0_987
	s_barrier
